# stack_i + trail half (waves 4-7) runs a K-loop copy whose SP2 A-fragment ds_reads are issued inside the preceding MFMA segment
# baseline (speedup 1.0000x reference)
; #define PG8_STAGE(bufoff, gbase, voff) do { const int so_ = (int)(unsigned)((const char*)(gbase) - base_##voff); _Pragma("unroll") for (int _i = 0; _i < 2; ++_i) \
;         __builtin_amdgcn_raw_ptr_buffer_load_lds(rs_##voff, (PG8_LAS unsigned*)(lds + (bufoff) + ldsw + _i * 8192), 16, (int)(voff)[_i], so_, 0, 0); } while (0)
; #define PG8_LDA(dst, b, h) do { _Pragma("unroll") for (int m = 0; m < 4; ++m) _Pragma("unroll") for (int k = 0; k < 2; ++k) dst[m][k] = *(const PG8_LAS bf16x8*)(lds + PG8_SA(b, h) + aoff + m * 2048 + k * 1024); } while (0)
; #define PG8_WAIT_V(n) asm volatile("s_waitcnt vmcnt(" #n ")" ::: "memory")
; #define PG8_WAIT_L(n) asm volatile("s_waitcnt lgkmcnt(" #n ")" ::: "memory")
; template <class Epi, class Sched, bool ALIGN_EPI = false, bool SP2 = false>
; __device__ __forceinline__ void gemm_phase(PG8_LAS unsigned char* lds, const Gemm g, const Sched& S, const Epi& E, int tid_in) {
;     ...
;         for (int t = 0; t < nt; t += 2) {
;             const bool last = (t == nt - 2);
;             const char* a1 = cA + (size_t)(t + 1) * kstep;
;             const char* a2 = last ? nA : cA + (size_t)(t + 2) * kstep; const char* b2 = last ? nB : cB + (size_t)(t + 2) * kstep;
;             const char* a3 = a2 + kstep; const char* b3 = b2 + kstep;
;             if (last && has_next) S.a_ready(nxt);
;             if constexpr (SP2) {
;             PG8_LDB(B0, 0, 0); PG8_LDB(B1, 0, 1); PG8_SCHED; PG8_LDA(At, 0, 0); PG8_STAGE(PG8_SA(1, 1), a1 + hstepA, voffA);
;             PG8_WAIT_V(8); PG8_WAIT_L(0); PG8_BAR; PG8_MMA(0, 0, At, B0); PG8_MMA(0, 1, At, B1); PG8_BAR; PG8_SCHED;
;             PG8_LDA(At, 0, 1); PG8_STAGE(PG8_SB(0, 0), b2, voffB); PG8_STAGE(PG8_SB(0, 1), b2 + hstepB, voffB); PG8_STAGE(PG8_SA(0, 0), a2, voffA);
;             PG8_WAIT_V(8); PG8_WAIT_L(0); PG8_BAR; PG8_MMA(1, 0, At, B0); PG8_MMA(1, 1, At, B1); PG8_BAR; PG8_SCHED;
;             PG8_LDB(B0, 1, 0); PG8_LDB(B1, 1, 1); PG8_SCHED; PG8_LDA(At, 1, 0); PG8_STAGE(PG8_SA(0, 1), a2 + hstepA, voffA);
;             PG8_WAIT_V(8); PG8_WAIT_L(0); PG8_BAR; PG8_MMA(0, 0, At, B0); PG8_MMA(0, 1, At, B1); PG8_BAR; PG8_SCHED;
;             PG8_LDA(At, 1, 1); PG8_STAGE(PG8_SB(1, 0), b3, voffB); PG8_STAGE(PG8_SB(1, 1), b3 + hstepB, voffB); PG8_STAGE(PG8_SA(1, 0), a3, voffA);
;             PG8_WAIT_V(8); PG8_WAIT_L(0); PG8_BAR; PG8_MMA(1, 0, At, B0); PG8_MMA(1, 1, At, B1); PG8_BAR; PG8_SCHED;
.Ltrl_loop0:
	v_add_u32_e32 v0, 0x10000, v237
	ds_read_b128 v[130:133], v0
	ds_read_b128 v[134:137], v0 offset:1024
	ds_read_b128 v[138:141], v0 offset:2048
	ds_read_b128 v[142:145], v0 offset:3072
	v_add_u32_e32 v0, 0x14000, v237
	ds_read_b128 v[146:149], v0
	ds_read_b128 v[150:153], v0 offset:1024
	ds_read_b128 v[154:157], v0 offset:2048
	ds_read_b128 v[158:161], v0 offset:3072
	s_add_u32 s16, s12, 0x100
	s_addc_u32 s17, s13, 0
	s_sub_i32 s12, s12, s4
	s_add_i32 s12, s12, 0x80080
	s_sub_i32 s36, s12, 0x80000
	s_cmp_eq_u32 s23, 28
	s_cselect_b32 s13, s19, s16
	s_mov_b32 m0, s69
	ds_read_b128 v[162:165], v238
	ds_read_b128 v[166:169], v238 offset:1024
	ds_read_b128 v[170:173], v238 offset:2048
	ds_read_b128 v[174:177], v238 offset:3072
	ds_read_b128 v[178:181], v238 offset:4096
	ds_read_b128 v[182:185], v238 offset:5120
	ds_read_b128 v[186:189], v238 offset:6144
	ds_read_b128 v[190:193], v238 offset:7168
	s_mov_b32 m0, s78
	s_nop 0
	buffer_load_dwordx4 v211, s[4:7], s36 offen lds
	s_mov_b32 m0, s69
	s_nop 0
	buffer_load_dwordx4 v195, s[4:7], s12 offen lds
	s_mov_b32 m0, s67
	s_nop 0
	buffer_load_dwordx4 v211, s[4:7], s12 offen lds
	s_waitcnt vmcnt(8)
	s_waitcnt lgkmcnt(0)
	s_setprio 1
	s_barrier
	v_mfma_f32_16x16x32_bf16 v[126:129], v[130:133], v[162:165], v[126:129]
	v_mfma_f32_16x16x32_bf16 v[122:125], v[138:141], v[162:165], v[122:125]
	v_mfma_f32_16x16x32_bf16 v[106:109], v[138:141], v[170:173], v[106:109]
	v_mfma_f32_16x16x32_bf16 v[110:113], v[130:133], v[170:173], v[110:113]
	v_mfma_f32_16x16x32_bf16 v[94:97], v[130:133], v[178:181], v[94:97]
	v_mfma_f32_16x16x32_bf16 v[90:93], v[138:141], v[178:181], v[90:93]
	v_mfma_f32_16x16x32_bf16 v[74:77], v[138:141], v[186:189], v[74:77]
	v_mfma_f32_16x16x32_bf16 v[78:81], v[130:133], v[186:189], v[78:81]
	v_mfma_f32_16x16x32_bf16 v[126:129], v[134:137], v[166:169], v[126:129]
	v_mfma_f32_16x16x32_bf16 v[122:125], v[142:145], v[166:169], v[122:125]
	v_mfma_f32_16x16x32_bf16 v[106:109], v[142:145], v[174:177], v[106:109]
	v_mfma_f32_16x16x32_bf16 v[110:113], v[134:137], v[174:177], v[110:113]
	v_mfma_f32_16x16x32_bf16 v[94:97], v[134:137], v[182:185], v[94:97]
	v_mfma_f32_16x16x32_bf16 v[90:93], v[142:145], v[182:185], v[90:93]
	v_mfma_f32_16x16x32_bf16 v[74:77], v[142:145], v[190:193], v[74:77]
	v_mfma_f32_16x16x32_bf16 v[78:81], v[134:137], v[190:193], v[78:81]
	v_mfma_f32_16x16x32_bf16 v[118:121], v[146:149], v[162:165], v[118:121]
	v_mfma_f32_16x16x32_bf16 v[114:117], v[154:157], v[162:165], v[114:117]
	ds_read_b128 v[162:165], v238 offset:16384
	v_mfma_f32_16x16x32_bf16 v[98:101], v[154:157], v[170:173], v[98:101]
	v_mfma_f32_16x16x32_bf16 v[102:105], v[146:149], v[170:173], v[102:105]
	ds_read_b128 v[170:173], v238 offset:18432
	v_mfma_f32_16x16x32_bf16 v[86:89], v[146:149], v[178:181], v[86:89]
	v_mfma_f32_16x16x32_bf16 v[82:85], v[154:157], v[178:181], v[82:85]
	ds_read_b128 v[178:181], v238 offset:20480
	v_mfma_f32_16x16x32_bf16 v[66:69], v[154:157], v[186:189], v[66:69]
	v_mfma_f32_16x16x32_bf16 v[70:73], v[146:149], v[186:189], v[70:73]
	ds_read_b128 v[186:189], v238 offset:22528
	v_mfma_f32_16x16x32_bf16 v[118:121], v[150:153], v[166:169], v[118:121]
	v_mfma_f32_16x16x32_bf16 v[114:117], v[158:161], v[166:169], v[114:117]
	ds_read_b128 v[166:169], v238 offset:17408
	v_mfma_f32_16x16x32_bf16 v[98:101], v[158:161], v[174:177], v[98:101]
	v_mfma_f32_16x16x32_bf16 v[102:105], v[150:153], v[174:177], v[102:105]
	ds_read_b128 v[174:177], v238 offset:19456
	v_mfma_f32_16x16x32_bf16 v[86:89], v[150:153], v[182:185], v[86:89]
	v_mfma_f32_16x16x32_bf16 v[82:85], v[158:161], v[182:185], v[82:85]
	ds_read_b128 v[182:185], v238 offset:21504
	v_mfma_f32_16x16x32_bf16 v[66:69], v[158:161], v[190:193], v[66:69]
	v_mfma_f32_16x16x32_bf16 v[70:73], v[150:153], v[190:193], v[70:73]
	ds_read_b128 v[190:193], v238 offset:23552
	s_barrier
	s_setprio 0
	s_cselect_b32 s12, s15, s20
	s_mov_b32 m0, s61
	s_mov_b32 s42, s6
	s_mov_b32 s43, s7
	s_sub_i32 s12, s12, s40
	buffer_load_dwordx4 v207, s[40:43], s12 offen lds
	s_mov_b32 m0, s62
	s_add_i32 s36, s12, 0x80000
	buffer_load_dwordx4 v224, s[40:43], s12 offen lds
	s_mov_b32 m0, s63
	s_sub_i32 s13, s13, s4
	buffer_load_dwordx4 v207, s[40:43], s36 offen lds
	s_mov_b32 m0, s71
	s_nop 0
	buffer_load_dwordx4 v224, s[40:43], s36 offen lds
	s_mov_b32 m0, s53
	s_nop 0
	buffer_load_dwordx4 v195, s[4:7], s13 offen lds
	s_waitcnt vmcnt(7)
	s_waitcnt lgkmcnt(0)
	s_setprio 1
	s_barrier
	v_mfma_f32_16x16x32_bf16 v[62:65], v[130:133], v[162:165], v[62:65]
	v_mfma_f32_16x16x32_bf16 v[58:61], v[138:141], v[162:165], v[58:61]
	v_mfma_f32_16x16x32_bf16 v[42:45], v[138:141], v[170:173], v[42:45]
	v_mfma_f32_16x16x32_bf16 v[46:49], v[130:133], v[170:173], v[46:49]
	v_mfma_f32_16x16x32_bf16 v[30:33], v[130:133], v[178:181], v[30:33]
	v_mfma_f32_16x16x32_bf16 v[26:29], v[138:141], v[178:181], v[26:29]
	v_mfma_f32_16x16x32_bf16 v[10:13], v[138:141], v[186:189], v[10:13]
	v_mfma_f32_16x16x32_bf16 v[14:17], v[130:133], v[186:189], v[14:17]
	v_mfma_f32_16x16x32_bf16 v[62:65], v[134:137], v[166:169], v[62:65]
	v_mfma_f32_16x16x32_bf16 v[58:61], v[142:145], v[166:169], v[58:61]
	v_mfma_f32_16x16x32_bf16 v[42:45], v[142:145], v[174:177], v[42:45]
	v_mfma_f32_16x16x32_bf16 v[46:49], v[134:137], v[174:177], v[46:49]
	v_mfma_f32_16x16x32_bf16 v[30:33], v[134:137], v[182:185], v[30:33]
	v_mfma_f32_16x16x32_bf16 v[26:29], v[142:145], v[182:185], v[26:29]
	v_mfma_f32_16x16x32_bf16 v[10:13], v[142:145], v[190:193], v[10:13]
	v_mfma_f32_16x16x32_bf16 v[14:17], v[134:137], v[190:193], v[14:17]
	v_mfma_f32_16x16x32_bf16 v[54:57], v[146:149], v[162:165], v[54:57]
	v_mfma_f32_16x16x32_bf16 v[50:53], v[154:157], v[162:165], v[50:53]
	v_mfma_f32_16x16x32_bf16 v[34:37], v[154:157], v[170:173], v[34:37]
	v_mfma_f32_16x16x32_bf16 v[38:41], v[146:149], v[170:173], v[38:41]
	v_mfma_f32_16x16x32_bf16 v[22:25], v[146:149], v[178:181], v[22:25]
	v_mfma_f32_16x16x32_bf16 v[18:21], v[154:157], v[178:181], v[18:21]
	v_mfma_f32_16x16x32_bf16 v[2:5], v[154:157], v[186:189], v[2:5]
	v_mfma_f32_16x16x32_bf16 v[6:9], v[146:149], v[186:189], v[6:9]
	v_mfma_f32_16x16x32_bf16 v[54:57], v[150:153], v[166:169], v[54:57]
	v_mfma_f32_16x16x32_bf16 v[50:53], v[158:161], v[166:169], v[50:53]
	v_mfma_f32_16x16x32_bf16 v[34:37], v[158:161], v[174:177], v[34:37]
	v_mfma_f32_16x16x32_bf16 v[38:41], v[150:153], v[174:177], v[38:41]
	v_mfma_f32_16x16x32_bf16 v[22:25], v[150:153], v[182:185], v[22:25]
	v_mfma_f32_16x16x32_bf16 v[18:21], v[158:161], v[182:185], v[18:21]
	v_mfma_f32_16x16x32_bf16 v[2:5], v[158:161], v[190:193], v[2:5]
	v_mfma_f32_16x16x32_bf16 v[6:9], v[150:153], v[190:193], v[6:9]
	s_barrier
; #define PG8_STAGE(bufoff, gbase, voff) do { const int so_ = (int)(unsigned)((const char*)(gbase) - base_##voff); _Pragma("unroll") for (int _i = 0; _i < 2; ++_i) \
;         __builtin_amdgcn_raw_ptr_buffer_load_lds(rs_##voff, (PG8_LAS unsigned*)(lds + (bufoff) + ldsw + _i * 8192), 16, (int)(voff)[_i], so_, 0, 0); } while (0)
; #define PG8_LDA(dst, b, h) do { _Pragma("unroll") for (int m = 0; m < 4; ++m) _Pragma("unroll") for (int k = 0; k < 2; ++k) dst[m][k] = *(const PG8_LAS bf16x8*)(lds + PG8_SA(b, h) + aoff + m * 2048 + k * 1024); } while (0)
; #define PG8_WAIT_V(n) asm volatile("s_waitcnt vmcnt(" #n ")" ::: "memory")
; #define PG8_WAIT_L(n) asm volatile("s_waitcnt lgkmcnt(" #n ")" ::: "memory")
; template <class Epi, class Sched, bool ALIGN_EPI = false, bool SP2 = false>
; __device__ __forceinline__ void gemm_phase(PG8_LAS unsigned char* lds, const Gemm g, const Sched& S, const Epi& E, int tid_in) {
;     ...
;         for (int t = 0; t < nt; t += 2) {
;             const bool last = (t == nt - 2);
;             const char* a1 = cA + (size_t)(t + 1) * kstep;
;             const char* a2 = last ? nA : cA + (size_t)(t + 2) * kstep; const char* b2 = last ? nB : cB + (size_t)(t + 2) * kstep;
;             const char* a3 = a2 + kstep; const char* b3 = b2 + kstep;
;             if (last && has_next) S.a_ready(nxt);
;             if constexpr (SP2) {
;             PG8_LDB(B0, 0, 0); PG8_LDB(B1, 0, 1); PG8_SCHED; PG8_LDA(At, 0, 0); PG8_STAGE(PG8_SA(1, 1), a1 + hstepA, voffA);
;             PG8_WAIT_V(8); PG8_WAIT_L(0); PG8_BAR; PG8_MMA(0, 0, At, B0); PG8_MMA(0, 1, At, B1); PG8_BAR; PG8_SCHED;
;             PG8_LDA(At, 0, 1); PG8_STAGE(PG8_SB(0, 0), b2, voffB); PG8_STAGE(PG8_SB(0, 1), b2 + hstepB, voffB); PG8_STAGE(PG8_SA(0, 0), a2, voffA);
;             PG8_WAIT_V(8); PG8_WAIT_L(0); PG8_BAR; PG8_MMA(1, 0, At, B0); PG8_MMA(1, 1, At, B1); PG8_BAR; PG8_SCHED;
;             PG8_LDB(B0, 1, 0); PG8_LDB(B1, 1, 1); PG8_SCHED; PG8_LDA(At, 1, 0); PG8_STAGE(PG8_SA(0, 1), a2 + hstepA, voffA);
;             PG8_WAIT_V(8); PG8_WAIT_L(0); PG8_BAR; PG8_MMA(0, 0, At, B0); PG8_MMA(0, 1, At, B1); PG8_BAR; PG8_SCHED;
;             PG8_LDA(At, 1, 1); PG8_STAGE(PG8_SB(1, 0), b3, voffB); PG8_STAGE(PG8_SB(1, 1), b3 + hstepB, voffB); PG8_STAGE(PG8_SA(1, 0), a3, voffA);
;             PG8_WAIT_V(8); PG8_WAIT_L(0); PG8_BAR; PG8_MMA(1, 0, At, B0); PG8_MMA(1, 1, At, B1); PG8_BAR; PG8_SCHED;
	s_setprio 0
	v_add_u32_e32 v0, 0x18000, v237
	ds_read_b128 v[130:133], v0
	ds_read_b128 v[134:137], v0 offset:1024
	ds_read_b128 v[138:141], v0 offset:2048
	ds_read_b128 v[142:145], v0 offset:3072
	v_add_u32_e32 v0, 0x1c000, v237
	ds_read_b128 v[146:149], v0
	ds_read_b128 v[150:153], v0 offset:1024
	ds_read_b128 v[154:157], v0 offset:2048
	ds_read_b128 v[158:161], v0 offset:3072
	s_add_i32 s36, s13, 0x80000
	s_mov_b32 m0, s73
	ds_read_b128 v[162:165], v238 offset:32768
	ds_read_b128 v[166:169], v238 offset:33792
	ds_read_b128 v[170:173], v238 offset:34816
	ds_read_b128 v[174:177], v238 offset:35840
	ds_read_b128 v[178:181], v238 offset:36864
	ds_read_b128 v[182:185], v238 offset:37888
	ds_read_b128 v[186:189], v238 offset:38912
	ds_read_b128 v[190:193], v238 offset:39936
	s_mov_b32 m0, s72
	s_nop 0
	buffer_load_dwordx4 v211, s[4:7], s13 offen lds
	s_mov_b32 m0, s73
	s_nop 0
	buffer_load_dwordx4 v195, s[4:7], s36 offen lds
	s_mov_b32 m0, s74
	s_nop 0
	buffer_load_dwordx4 v211, s[4:7], s36 offen lds
	s_waitcnt vmcnt(8)
	s_waitcnt lgkmcnt(0)
	s_setprio 1
	s_barrier
	v_mfma_f32_16x16x32_bf16 v[126:129], v[130:133], v[162:165], v[126:129]
	v_mfma_f32_16x16x32_bf16 v[122:125], v[138:141], v[162:165], v[122:125]
	v_mfma_f32_16x16x32_bf16 v[106:109], v[138:141], v[170:173], v[106:109]
	v_mfma_f32_16x16x32_bf16 v[110:113], v[130:133], v[170:173], v[110:113]
	v_mfma_f32_16x16x32_bf16 v[94:97], v[130:133], v[178:181], v[94:97]
	v_mfma_f32_16x16x32_bf16 v[90:93], v[138:141], v[178:181], v[90:93]
	v_mfma_f32_16x16x32_bf16 v[74:77], v[138:141], v[186:189], v[74:77]
	v_mfma_f32_16x16x32_bf16 v[78:81], v[130:133], v[186:189], v[78:81]
	v_mfma_f32_16x16x32_bf16 v[126:129], v[134:137], v[166:169], v[126:129]
	v_mfma_f32_16x16x32_bf16 v[122:125], v[142:145], v[166:169], v[122:125]
	v_mfma_f32_16x16x32_bf16 v[106:109], v[142:145], v[174:177], v[106:109]
	v_mfma_f32_16x16x32_bf16 v[110:113], v[134:137], v[174:177], v[110:113]
	v_mfma_f32_16x16x32_bf16 v[94:97], v[134:137], v[182:185], v[94:97]
	v_mfma_f32_16x16x32_bf16 v[90:93], v[142:145], v[182:185], v[90:93]
	v_mfma_f32_16x16x32_bf16 v[74:77], v[142:145], v[190:193], v[74:77]
	v_mfma_f32_16x16x32_bf16 v[78:81], v[134:137], v[190:193], v[78:81]
	v_mfma_f32_16x16x32_bf16 v[118:121], v[146:149], v[162:165], v[118:121]
	v_mfma_f32_16x16x32_bf16 v[114:117], v[154:157], v[162:165], v[114:117]
	ds_read_b128 v[162:165], v238 offset:49152
	v_mfma_f32_16x16x32_bf16 v[98:101], v[154:157], v[170:173], v[98:101]
	v_mfma_f32_16x16x32_bf16 v[102:105], v[146:149], v[170:173], v[102:105]
	ds_read_b128 v[170:173], v238 offset:51200
	v_mfma_f32_16x16x32_bf16 v[86:89], v[146:149], v[178:181], v[86:89]
	v_mfma_f32_16x16x32_bf16 v[82:85], v[154:157], v[178:181], v[82:85]
	ds_read_b128 v[178:181], v238 offset:53248
	v_mfma_f32_16x16x32_bf16 v[66:69], v[154:157], v[186:189], v[66:69]
	v_mfma_f32_16x16x32_bf16 v[70:73], v[146:149], v[186:189], v[70:73]
	ds_read_b128 v[186:189], v238 offset:55296
	v_mfma_f32_16x16x32_bf16 v[118:121], v[150:153], v[166:169], v[118:121]
	v_mfma_f32_16x16x32_bf16 v[114:117], v[158:161], v[166:169], v[114:117]
	ds_read_b128 v[166:169], v238 offset:50176
	v_mfma_f32_16x16x32_bf16 v[98:101], v[158:161], v[174:177], v[98:101]
	v_mfma_f32_16x16x32_bf16 v[102:105], v[150:153], v[174:177], v[102:105]
	ds_read_b128 v[174:177], v238 offset:52224
	v_mfma_f32_16x16x32_bf16 v[86:89], v[150:153], v[182:185], v[86:89]
	v_mfma_f32_16x16x32_bf16 v[82:85], v[158:161], v[182:185], v[82:85]
	ds_read_b128 v[182:185], v238 offset:54272
	v_mfma_f32_16x16x32_bf16 v[66:69], v[158:161], v[190:193], v[66:69]
	v_mfma_f32_16x16x32_bf16 v[70:73], v[150:153], v[190:193], v[70:73]
	ds_read_b128 v[190:193], v238 offset:56320
	s_barrier
	s_setprio 0
	s_mov_b32 m0, s75
	s_add_i32 s36, s12, 0x80
	buffer_load_dwordx4 v207, s[40:43], s36 offen lds
	s_mov_b32 m0, s76
	s_add_i32 s12, s12, 0x80080
	buffer_load_dwordx4 v224, s[40:43], s36 offen lds
	s_mov_b32 m0, s79
	s_addk_i32 s13, 0x80
	buffer_load_dwordx4 v207, s[40:43], s12 offen lds
	s_mov_b32 m0, s68
	s_nop 0
	buffer_load_dwordx4 v224, s[40:43], s12 offen lds
	s_mov_b32 m0, s77
	s_nop 0
	buffer_load_dwordx4 v195, s[4:7], s13 offen lds
	s_waitcnt vmcnt(7)
	s_waitcnt lgkmcnt(0)
	s_setprio 1
	s_barrier
	v_mfma_f32_16x16x32_bf16 v[62:65], v[130:133], v[162:165], v[62:65]
	v_mfma_f32_16x16x32_bf16 v[58:61], v[138:141], v[162:165], v[58:61]
	v_mfma_f32_16x16x32_bf16 v[42:45], v[138:141], v[170:173], v[42:45]
	v_mfma_f32_16x16x32_bf16 v[46:49], v[130:133], v[170:173], v[46:49]
	v_mfma_f32_16x16x32_bf16 v[30:33], v[130:133], v[178:181], v[30:33]
	v_mfma_f32_16x16x32_bf16 v[26:29], v[138:141], v[178:181], v[26:29]
	v_mfma_f32_16x16x32_bf16 v[10:13], v[138:141], v[186:189], v[10:13]
	v_mfma_f32_16x16x32_bf16 v[14:17], v[130:133], v[186:189], v[14:17]
	v_mfma_f32_16x16x32_bf16 v[62:65], v[134:137], v[166:169], v[62:65]
	v_mfma_f32_16x16x32_bf16 v[58:61], v[142:145], v[166:169], v[58:61]
	v_mfma_f32_16x16x32_bf16 v[42:45], v[142:145], v[174:177], v[42:45]
	v_mfma_f32_16x16x32_bf16 v[46:49], v[134:137], v[174:177], v[46:49]
	v_mfma_f32_16x16x32_bf16 v[30:33], v[134:137], v[182:185], v[30:33]
	v_mfma_f32_16x16x32_bf16 v[26:29], v[142:145], v[182:185], v[26:29]
	v_mfma_f32_16x16x32_bf16 v[10:13], v[142:145], v[190:193], v[10:13]
	v_mfma_f32_16x16x32_bf16 v[14:17], v[134:137], v[190:193], v[14:17]
	v_mfma_f32_16x16x32_bf16 v[54:57], v[146:149], v[162:165], v[54:57]
	v_mfma_f32_16x16x32_bf16 v[50:53], v[154:157], v[162:165], v[50:53]
	v_mfma_f32_16x16x32_bf16 v[34:37], v[154:157], v[170:173], v[34:37]
	v_mfma_f32_16x16x32_bf16 v[38:41], v[146:149], v[170:173], v[38:41]
	v_mfma_f32_16x16x32_bf16 v[22:25], v[146:149], v[178:181], v[22:25]
	v_mfma_f32_16x16x32_bf16 v[18:21], v[154:157], v[178:181], v[18:21]
	v_mfma_f32_16x16x32_bf16 v[2:5], v[154:157], v[186:189], v[2:5]
	v_mfma_f32_16x16x32_bf16 v[6:9], v[146:149], v[186:189], v[6:9]
	v_mfma_f32_16x16x32_bf16 v[54:57], v[150:153], v[166:169], v[54:57]
	v_mfma_f32_16x16x32_bf16 v[50:53], v[158:161], v[166:169], v[50:53]
	v_mfma_f32_16x16x32_bf16 v[34:37], v[158:161], v[174:177], v[34:37]
	v_mfma_f32_16x16x32_bf16 v[38:41], v[150:153], v[174:177], v[38:41]
	v_mfma_f32_16x16x32_bf16 v[22:25], v[150:153], v[182:185], v[22:25]
	v_mfma_f32_16x16x32_bf16 v[18:21], v[158:161], v[182:185], v[18:21]
	v_mfma_f32_16x16x32_bf16 v[2:5], v[158:161], v[190:193], v[2:5]
	v_mfma_f32_16x16x32_bf16 v[6:9], v[150:153], v[190:193], v[6:9]
	s_barrier
	s_setprio 0
	s_add_i32 s23, s23, 2
	s_add_u32 s20, s20, 0x100
	s_addc_u32 s21, s21, 0
	s_cmp_gt_u32 s23, 29
	s_mov_b64 s[12:13], s[16:17]
	s_cbranch_scc0 .Ltrl_loop0

; #define PG8_STAGE(bufoff, gbase, voff) do { const int so_ = (int)(unsigned)((const char*)(gbase) - base_##voff); _Pragma("unroll") for (int _i = 0; _i < 2; ++_i) \
;         __builtin_amdgcn_raw_ptr_buffer_load_lds(rs_##voff, (PG8_LAS unsigned*)(lds + (bufoff) + ldsw + _i * 8192), 16, (int)(voff)[_i], so_, 0, 0); } while (0)
; #define PG8_LDA(dst, b, h) do { _Pragma("unroll") for (int m = 0; m < 4; ++m) _Pragma("unroll") for (int k = 0; k < 2; ++k) dst[m][k] = *(const PG8_LAS bf16x8*)(lds + PG8_SA(b, h) + aoff + m * 2048 + k * 1024); } while (0)
; #define PG8_WAIT_V(n) asm volatile("s_waitcnt vmcnt(" #n ")" ::: "memory")
; #define PG8_WAIT_L(n) asm volatile("s_waitcnt lgkmcnt(" #n ")" ::: "memory")
; template <class Epi, class Sched, bool ALIGN_EPI = false, bool SP2 = false>
; __device__ __forceinline__ void gemm_phase(PG8_LAS unsigned char* lds, const Gemm g, const Sched& S, const Epi& E, int tid_in) {
;     ...
;         for (int t = 0; t < nt; t += 2) {
;             const bool last = (t == nt - 2);
;             const char* a1 = cA + (size_t)(t + 1) * kstep;
;             const char* a2 = last ? nA : cA + (size_t)(t + 2) * kstep; const char* b2 = last ? nB : cB + (size_t)(t + 2) * kstep;
;             const char* a3 = a2 + kstep; const char* b3 = b2 + kstep;
;             if (last && has_next) S.a_ready(nxt);
;             if constexpr (SP2) {
;             PG8_LDB(B0, 0, 0); PG8_LDB(B1, 0, 1); PG8_SCHED; PG8_LDA(At, 0, 0); PG8_STAGE(PG8_SA(1, 1), a1 + hstepA, voffA);
;             PG8_WAIT_V(8); PG8_WAIT_L(0); PG8_BAR; PG8_MMA(0, 0, At, B0); PG8_MMA(0, 1, At, B1); PG8_BAR; PG8_SCHED;
;             PG8_LDA(At, 0, 1); PG8_STAGE(PG8_SB(0, 0), b2, voffB); PG8_STAGE(PG8_SB(0, 1), b2 + hstepB, voffB); PG8_STAGE(PG8_SA(0, 0), a2, voffA);
;             PG8_WAIT_V(8); PG8_WAIT_L(0); PG8_BAR; PG8_MMA(1, 0, At, B0); PG8_MMA(1, 1, At, B1); PG8_BAR; PG8_SCHED;
;             PG8_LDB(B0, 1, 0); PG8_LDB(B1, 1, 1); PG8_SCHED; PG8_LDA(At, 1, 0); PG8_STAGE(PG8_SA(0, 1), a2 + hstepA, voffA);
;             PG8_WAIT_V(8); PG8_WAIT_L(0); PG8_BAR; PG8_MMA(0, 0, At, B0); PG8_MMA(0, 1, At, B1); PG8_BAR; PG8_SCHED;
;             PG8_LDA(At, 1, 1); PG8_STAGE(PG8_SB(1, 0), b3, voffB); PG8_STAGE(PG8_SB(1, 1), b3 + hstepB, voffB); PG8_STAGE(PG8_SA(1, 0), a3, voffA);
;             PG8_WAIT_V(8); PG8_WAIT_L(0); PG8_BAR; PG8_MMA(1, 0, At, B0); PG8_MMA(1, 1, At, B1); PG8_BAR; PG8_SCHED;
.Ltrl_loop1:
	v_add_u32_e32 v0, 0x10000, v236
	ds_read_b128 v[132:135], v0
	ds_read_b128 v[136:139], v0 offset:1024
	ds_read_b128 v[140:143], v0 offset:2048
	ds_read_b128 v[144:147], v0 offset:3072
	v_add_u32_e32 v0, 0x14000, v236
	ds_read_b128 v[148:151], v0
	ds_read_b128 v[152:155], v0 offset:1024
	ds_read_b128 v[156:159], v0 offset:2048
	ds_read_b128 v[160:163], v0 offset:3072
	s_add_u32 s16, s12, 0x100
	s_addc_u32 s17, s13, 0
	s_sub_i32 s12, s12, s4
	s_add_i32 s12, s12, 0xc0080
	s_sub_i32 s39, s12, 0xc0000
	s_cmp_eq_u32 s38, 12
	s_cselect_b32 s13, s24, s16
	s_mov_b32 m0, s76
	ds_read_b128 v[164:167], v237
	ds_read_b128 v[168:171], v237 offset:1024
	ds_read_b128 v[172:175], v237 offset:2048
	ds_read_b128 v[176:179], v237 offset:3072
	ds_read_b128 v[180:183], v237 offset:4096
	ds_read_b128 v[184:187], v237 offset:5120
	ds_read_b128 v[188:191], v237 offset:6144
	ds_read_b128 v[192:195], v237 offset:7168
	s_mov_b32 m0, s73
	s_nop 0
	buffer_load_dwordx4 v222, s[4:7], s39 offen lds
	s_mov_b32 m0, s76
	s_nop 0
	buffer_load_dwordx4 v220, s[4:7], s12 offen lds
	s_mov_b32 m0, s77
	s_nop 0
	buffer_load_dwordx4 v222, s[4:7], s12 offen lds
	s_waitcnt vmcnt(8)
	s_waitcnt lgkmcnt(0)
	s_setprio 1
	s_barrier
	v_mfma_f32_16x16x32_bf16 v[128:131], v[132:135], v[164:167], v[128:131]
	v_mfma_f32_16x16x32_bf16 v[124:127], v[140:143], v[164:167], v[124:127]
	v_mfma_f32_16x16x32_bf16 v[116:119], v[140:143], v[172:175], v[116:119]
	v_mfma_f32_16x16x32_bf16 v[120:123], v[132:135], v[172:175], v[120:123]
	v_mfma_f32_16x16x32_bf16 v[112:115], v[132:135], v[180:183], v[112:115]
	v_mfma_f32_16x16x32_bf16 v[108:111], v[140:143], v[180:183], v[108:111]
	v_mfma_f32_16x16x32_bf16 v[100:103], v[140:143], v[188:191], v[100:103]
	v_mfma_f32_16x16x32_bf16 v[104:107], v[132:135], v[188:191], v[104:107]
	v_mfma_f32_16x16x32_bf16 v[128:131], v[136:139], v[168:171], v[128:131]
	v_mfma_f32_16x16x32_bf16 v[124:127], v[144:147], v[168:171], v[124:127]
	v_mfma_f32_16x16x32_bf16 v[116:119], v[144:147], v[176:179], v[116:119]
	v_mfma_f32_16x16x32_bf16 v[120:123], v[136:139], v[176:179], v[120:123]
	v_mfma_f32_16x16x32_bf16 v[112:115], v[136:139], v[184:187], v[112:115]
	v_mfma_f32_16x16x32_bf16 v[108:111], v[144:147], v[184:187], v[108:111]
	v_mfma_f32_16x16x32_bf16 v[100:103], v[144:147], v[192:195], v[100:103]
	v_mfma_f32_16x16x32_bf16 v[104:107], v[136:139], v[192:195], v[104:107]
	v_mfma_f32_16x16x32_bf16 v[96:99], v[148:151], v[164:167], v[96:99]
	v_mfma_f32_16x16x32_bf16 v[92:95], v[156:159], v[164:167], v[92:95]
	ds_read_b128 v[164:167], v237 offset:16384
	v_mfma_f32_16x16x32_bf16 v[84:87], v[156:159], v[172:175], v[84:87]
	v_mfma_f32_16x16x32_bf16 v[88:91], v[148:151], v[172:175], v[88:91]
	ds_read_b128 v[172:175], v237 offset:18432
	v_mfma_f32_16x16x32_bf16 v[80:83], v[148:151], v[180:183], v[80:83]
	v_mfma_f32_16x16x32_bf16 v[76:79], v[156:159], v[180:183], v[76:79]
	ds_read_b128 v[180:183], v237 offset:20480
	v_mfma_f32_16x16x32_bf16 v[68:71], v[156:159], v[188:191], v[68:71]
	v_mfma_f32_16x16x32_bf16 v[72:75], v[148:151], v[188:191], v[72:75]
	ds_read_b128 v[188:191], v237 offset:22528
	v_mfma_f32_16x16x32_bf16 v[96:99], v[152:155], v[168:171], v[96:99]
	v_mfma_f32_16x16x32_bf16 v[92:95], v[160:163], v[168:171], v[92:95]
	ds_read_b128 v[168:171], v237 offset:17408
	v_mfma_f32_16x16x32_bf16 v[84:87], v[160:163], v[176:179], v[84:87]
	v_mfma_f32_16x16x32_bf16 v[88:91], v[152:155], v[176:179], v[88:91]
	ds_read_b128 v[176:179], v237 offset:19456
	v_mfma_f32_16x16x32_bf16 v[80:83], v[152:155], v[184:187], v[80:83]
	v_mfma_f32_16x16x32_bf16 v[76:79], v[160:163], v[184:187], v[76:79]
	ds_read_b128 v[184:187], v237 offset:21504
	v_mfma_f32_16x16x32_bf16 v[68:71], v[160:163], v[192:195], v[68:71]
	v_mfma_f32_16x16x32_bf16 v[72:75], v[152:155], v[192:195], v[72:75]
	ds_read_b128 v[192:195], v237 offset:23552
	s_barrier
	s_setprio 0
	s_cselect_b32 s12, s18, s19
	s_mov_b32 m0, s26
	s_mov_b32 s46, s6
	s_mov_b32 s47, s7
	s_sub_i32 s12, s12, s44
	buffer_load_dwordx4 v221, s[44:47], s12 offen lds
	s_mov_b32 m0, s53
	s_add_i32 s39, s12, 0x40000
	buffer_load_dwordx4 v223, s[44:47], s12 offen lds
	s_mov_b32 m0, s60
	s_sub_i32 s13, s13, s4
	buffer_load_dwordx4 v221, s[44:47], s39 offen lds
	s_mov_b32 m0, s61
	s_nop 0
	buffer_load_dwordx4 v223, s[44:47], s39 offen lds
	s_mov_b32 m0, s21
	s_nop 0
	buffer_load_dwordx4 v220, s[4:7], s13 offen lds
	s_waitcnt vmcnt(7)
	s_waitcnt lgkmcnt(0)
	s_setprio 1
	s_barrier
	v_mfma_f32_16x16x32_bf16 v[64:67], v[132:135], v[164:167], v[64:67]
	v_mfma_f32_16x16x32_bf16 v[60:63], v[140:143], v[164:167], v[60:63]
	v_mfma_f32_16x16x32_bf16 v[52:55], v[140:143], v[172:175], v[52:55]
	v_mfma_f32_16x16x32_bf16 v[56:59], v[132:135], v[172:175], v[56:59]
	v_mfma_f32_16x16x32_bf16 v[48:51], v[132:135], v[180:183], v[48:51]
	v_mfma_f32_16x16x32_bf16 v[44:47], v[140:143], v[180:183], v[44:47]
	v_mfma_f32_16x16x32_bf16 v[36:39], v[140:143], v[188:191], v[36:39]
	v_mfma_f32_16x16x32_bf16 v[40:43], v[132:135], v[188:191], v[40:43]
	v_mfma_f32_16x16x32_bf16 v[64:67], v[136:139], v[168:171], v[64:67]
	v_mfma_f32_16x16x32_bf16 v[60:63], v[144:147], v[168:171], v[60:63]
	v_mfma_f32_16x16x32_bf16 v[52:55], v[144:147], v[176:179], v[52:55]
	v_mfma_f32_16x16x32_bf16 v[56:59], v[136:139], v[176:179], v[56:59]
	v_mfma_f32_16x16x32_bf16 v[48:51], v[136:139], v[184:187], v[48:51]
	v_mfma_f32_16x16x32_bf16 v[44:47], v[144:147], v[184:187], v[44:47]
	v_mfma_f32_16x16x32_bf16 v[36:39], v[144:147], v[192:195], v[36:39]
	v_mfma_f32_16x16x32_bf16 v[40:43], v[136:139], v[192:195], v[40:43]
	v_mfma_f32_16x16x32_bf16 v[32:35], v[148:151], v[164:167], v[32:35]
	v_mfma_f32_16x16x32_bf16 v[28:31], v[156:159], v[164:167], v[28:31]
	v_mfma_f32_16x16x32_bf16 v[20:23], v[156:159], v[172:175], v[20:23]
	v_mfma_f32_16x16x32_bf16 v[24:27], v[148:151], v[172:175], v[24:27]
	v_mfma_f32_16x16x32_bf16 v[16:19], v[148:151], v[180:183], v[16:19]
	v_mfma_f32_16x16x32_bf16 v[12:15], v[156:159], v[180:183], v[12:15]
	v_mfma_f32_16x16x32_bf16 v[2:5], v[156:159], v[188:191], v[4:7]
	v_mfma_f32_16x16x32_bf16 v[8:11], v[148:151], v[188:191], v[8:11]
	v_mfma_f32_16x16x32_bf16 v[32:35], v[152:155], v[168:171], v[32:35]
	v_mfma_f32_16x16x32_bf16 v[28:31], v[160:163], v[168:171], v[28:31]
	v_mfma_f32_16x16x32_bf16 v[20:23], v[160:163], v[176:179], v[20:23]
	v_mfma_f32_16x16x32_bf16 v[24:27], v[152:155], v[176:179], v[24:27]
	v_mfma_f32_16x16x32_bf16 v[16:19], v[152:155], v[184:187], v[16:19]
	v_mfma_f32_16x16x32_bf16 v[12:15], v[160:163], v[184:187], v[12:15]
	v_mfma_f32_16x16x32_bf16 v[2:5], v[160:163], v[192:195], v[2:5]
	v_mfma_f32_16x16x32_bf16 v[8:11], v[152:155], v[192:195], v[8:11]
	s_barrier
; #define PG8_STAGE(bufoff, gbase, voff) do { const int so_ = (int)(unsigned)((const char*)(gbase) - base_##voff); _Pragma("unroll") for (int _i = 0; _i < 2; ++_i) \
;         __builtin_amdgcn_raw_ptr_buffer_load_lds(rs_##voff, (PG8_LAS unsigned*)(lds + (bufoff) + ldsw + _i * 8192), 16, (int)(voff)[_i], so_, 0, 0); } while (0)
; #define PG8_LDA(dst, b, h) do { _Pragma("unroll") for (int m = 0; m < 4; ++m) _Pragma("unroll") for (int k = 0; k < 2; ++k) dst[m][k] = *(const PG8_LAS bf16x8*)(lds + PG8_SA(b, h) + aoff + m * 2048 + k * 1024); } while (0)
; #define PG8_WAIT_V(n) asm volatile("s_waitcnt vmcnt(" #n ")" ::: "memory")
; #define PG8_WAIT_L(n) asm volatile("s_waitcnt lgkmcnt(" #n ")" ::: "memory")
; template <class Epi, class Sched, bool ALIGN_EPI = false, bool SP2 = false>
; __device__ __forceinline__ void gemm_phase(PG8_LAS unsigned char* lds, const Gemm g, const Sched& S, const Epi& E, int tid_in) {
;     ...
;         for (int t = 0; t < nt; t += 2) {
;             const bool last = (t == nt - 2);
;             const char* a1 = cA + (size_t)(t + 1) * kstep;
;             const char* a2 = last ? nA : cA + (size_t)(t + 2) * kstep; const char* b2 = last ? nB : cB + (size_t)(t + 2) * kstep;
;             const char* a3 = a2 + kstep; const char* b3 = b2 + kstep;
;             if (last && has_next) S.a_ready(nxt);
;             if constexpr (SP2) {
;             PG8_LDB(B0, 0, 0); PG8_LDB(B1, 0, 1); PG8_SCHED; PG8_LDA(At, 0, 0); PG8_STAGE(PG8_SA(1, 1), a1 + hstepA, voffA);
;             PG8_WAIT_V(8); PG8_WAIT_L(0); PG8_BAR; PG8_MMA(0, 0, At, B0); PG8_MMA(0, 1, At, B1); PG8_BAR; PG8_SCHED;
;             PG8_LDA(At, 0, 1); PG8_STAGE(PG8_SB(0, 0), b2, voffB); PG8_STAGE(PG8_SB(0, 1), b2 + hstepB, voffB); PG8_STAGE(PG8_SA(0, 0), a2, voffA);
;             PG8_WAIT_V(8); PG8_WAIT_L(0); PG8_BAR; PG8_MMA(1, 0, At, B0); PG8_MMA(1, 1, At, B1); PG8_BAR; PG8_SCHED;
;             PG8_LDB(B0, 1, 0); PG8_LDB(B1, 1, 1); PG8_SCHED; PG8_LDA(At, 1, 0); PG8_STAGE(PG8_SA(0, 1), a2 + hstepA, voffA);
;             PG8_WAIT_V(8); PG8_WAIT_L(0); PG8_BAR; PG8_MMA(0, 0, At, B0); PG8_MMA(0, 1, At, B1); PG8_BAR; PG8_SCHED;
;             PG8_LDA(At, 1, 1); PG8_STAGE(PG8_SB(1, 0), b3, voffB); PG8_STAGE(PG8_SB(1, 1), b3 + hstepB, voffB); PG8_STAGE(PG8_SA(1, 0), a3, voffA);
;             PG8_WAIT_V(8); PG8_WAIT_L(0); PG8_BAR; PG8_MMA(1, 0, At, B0); PG8_MMA(1, 1, At, B1); PG8_BAR; PG8_SCHED;
	s_setprio 0
	v_add_u32_e32 v0, 0x18000, v236
	ds_read_b128 v[132:135], v0
	ds_read_b128 v[136:139], v0 offset:1024
	ds_read_b128 v[140:143], v0 offset:2048
	ds_read_b128 v[144:147], v0 offset:3072
	v_add_u32_e32 v0, 0x1c000, v236
	ds_read_b128 v[148:151], v0
	ds_read_b128 v[152:155], v0 offset:1024
	ds_read_b128 v[156:159], v0 offset:2048
	ds_read_b128 v[160:163], v0 offset:3072
	s_add_i32 s39, s13, 0xc0000
	s_mov_b32 m0, s63
	ds_read_b128 v[164:167], v237 offset:32768
	ds_read_b128 v[168:171], v237 offset:33792
	ds_read_b128 v[172:175], v237 offset:34816
	ds_read_b128 v[176:179], v237 offset:35840
	ds_read_b128 v[180:183], v237 offset:36864
	ds_read_b128 v[184:187], v237 offset:37888
	ds_read_b128 v[188:191], v237 offset:38912
	ds_read_b128 v[192:195], v237 offset:39936
	s_mov_b32 m0, s62
	s_nop 0
	buffer_load_dwordx4 v222, s[4:7], s13 offen lds
	s_mov_b32 m0, s63
	s_nop 0
	buffer_load_dwordx4 v220, s[4:7], s39 offen lds
	s_mov_b32 m0, s66
	s_nop 0
	buffer_load_dwordx4 v222, s[4:7], s39 offen lds
	s_waitcnt vmcnt(8)
	s_waitcnt lgkmcnt(0)
	s_setprio 1
	s_barrier
	v_mfma_f32_16x16x32_bf16 v[128:131], v[132:135], v[164:167], v[128:131]
	v_mfma_f32_16x16x32_bf16 v[124:127], v[140:143], v[164:167], v[124:127]
	v_mfma_f32_16x16x32_bf16 v[116:119], v[140:143], v[172:175], v[116:119]
	v_mfma_f32_16x16x32_bf16 v[120:123], v[132:135], v[172:175], v[120:123]
	v_mfma_f32_16x16x32_bf16 v[112:115], v[132:135], v[180:183], v[112:115]
	v_mfma_f32_16x16x32_bf16 v[108:111], v[140:143], v[180:183], v[108:111]
	v_mfma_f32_16x16x32_bf16 v[100:103], v[140:143], v[188:191], v[100:103]
	v_mfma_f32_16x16x32_bf16 v[104:107], v[132:135], v[188:191], v[104:107]
	v_mfma_f32_16x16x32_bf16 v[128:131], v[136:139], v[168:171], v[128:131]
	v_mfma_f32_16x16x32_bf16 v[124:127], v[144:147], v[168:171], v[124:127]
	v_mfma_f32_16x16x32_bf16 v[116:119], v[144:147], v[176:179], v[116:119]
	v_mfma_f32_16x16x32_bf16 v[120:123], v[136:139], v[176:179], v[120:123]
	v_mfma_f32_16x16x32_bf16 v[112:115], v[136:139], v[184:187], v[112:115]
	v_mfma_f32_16x16x32_bf16 v[108:111], v[144:147], v[184:187], v[108:111]
	v_mfma_f32_16x16x32_bf16 v[100:103], v[144:147], v[192:195], v[100:103]
	v_mfma_f32_16x16x32_bf16 v[104:107], v[136:139], v[192:195], v[104:107]
	v_mfma_f32_16x16x32_bf16 v[96:99], v[148:151], v[164:167], v[96:99]
	v_mfma_f32_16x16x32_bf16 v[92:95], v[156:159], v[164:167], v[92:95]
	ds_read_b128 v[164:167], v237 offset:49152
	v_mfma_f32_16x16x32_bf16 v[84:87], v[156:159], v[172:175], v[84:87]
	v_mfma_f32_16x16x32_bf16 v[88:91], v[148:151], v[172:175], v[88:91]
	ds_read_b128 v[172:175], v237 offset:51200
	v_mfma_f32_16x16x32_bf16 v[80:83], v[148:151], v[180:183], v[80:83]
	v_mfma_f32_16x16x32_bf16 v[76:79], v[156:159], v[180:183], v[76:79]
	ds_read_b128 v[180:183], v237 offset:53248
	v_mfma_f32_16x16x32_bf16 v[68:71], v[156:159], v[188:191], v[68:71]
	v_mfma_f32_16x16x32_bf16 v[72:75], v[148:151], v[188:191], v[72:75]
	ds_read_b128 v[188:191], v237 offset:55296
	v_mfma_f32_16x16x32_bf16 v[96:99], v[152:155], v[168:171], v[96:99]
	v_mfma_f32_16x16x32_bf16 v[92:95], v[160:163], v[168:171], v[92:95]
	ds_read_b128 v[168:171], v237 offset:50176
	v_mfma_f32_16x16x32_bf16 v[84:87], v[160:163], v[176:179], v[84:87]
	v_mfma_f32_16x16x32_bf16 v[88:91], v[152:155], v[176:179], v[88:91]
	ds_read_b128 v[176:179], v237 offset:52224
	v_mfma_f32_16x16x32_bf16 v[80:83], v[152:155], v[184:187], v[80:83]
	v_mfma_f32_16x16x32_bf16 v[76:79], v[160:163], v[184:187], v[76:79]
	ds_read_b128 v[184:187], v237 offset:54272
	v_mfma_f32_16x16x32_bf16 v[68:71], v[160:163], v[192:195], v[68:71]
	v_mfma_f32_16x16x32_bf16 v[72:75], v[152:155], v[192:195], v[72:75]
	ds_read_b128 v[192:195], v237 offset:56320
	s_barrier
	s_setprio 0
	s_mov_b32 m0, s69
	s_add_i32 s39, s12, 0x80
	buffer_load_dwordx4 v221, s[44:47], s39 offen lds
	s_mov_b32 m0, s71
	s_add_i32 s12, s12, 0x40080
	buffer_load_dwordx4 v223, s[44:47], s39 offen lds
	s_mov_b32 m0, s74
	s_addk_i32 s13, 0x80
	buffer_load_dwordx4 v221, s[44:47], s12 offen lds
	s_mov_b32 m0, s75
	s_nop 0
	buffer_load_dwordx4 v223, s[44:47], s12 offen lds
	s_mov_b32 m0, s72
	s_nop 0
	buffer_load_dwordx4 v220, s[4:7], s13 offen lds
	s_waitcnt vmcnt(7)
	s_waitcnt lgkmcnt(0)
	s_setprio 1
	s_barrier
	v_mfma_f32_16x16x32_bf16 v[64:67], v[132:135], v[164:167], v[64:67]
	v_mfma_f32_16x16x32_bf16 v[60:63], v[140:143], v[164:167], v[60:63]
	v_mfma_f32_16x16x32_bf16 v[52:55], v[140:143], v[172:175], v[52:55]
	v_mfma_f32_16x16x32_bf16 v[56:59], v[132:135], v[172:175], v[56:59]
	v_mfma_f32_16x16x32_bf16 v[48:51], v[132:135], v[180:183], v[48:51]
	v_mfma_f32_16x16x32_bf16 v[44:47], v[140:143], v[180:183], v[44:47]
	v_mfma_f32_16x16x32_bf16 v[36:39], v[140:143], v[188:191], v[36:39]
	v_mfma_f32_16x16x32_bf16 v[40:43], v[132:135], v[188:191], v[40:43]
	v_mfma_f32_16x16x32_bf16 v[64:67], v[136:139], v[168:171], v[64:67]
	v_mfma_f32_16x16x32_bf16 v[60:63], v[144:147], v[168:171], v[60:63]
	v_mfma_f32_16x16x32_bf16 v[52:55], v[144:147], v[176:179], v[52:55]
	v_mfma_f32_16x16x32_bf16 v[56:59], v[136:139], v[176:179], v[56:59]
	v_mfma_f32_16x16x32_bf16 v[48:51], v[136:139], v[184:187], v[48:51]
	v_mfma_f32_16x16x32_bf16 v[44:47], v[144:147], v[184:187], v[44:47]
	v_mfma_f32_16x16x32_bf16 v[36:39], v[144:147], v[192:195], v[36:39]
	v_mfma_f32_16x16x32_bf16 v[40:43], v[136:139], v[192:195], v[40:43]
	v_mfma_f32_16x16x32_bf16 v[32:35], v[148:151], v[164:167], v[32:35]
	v_mfma_f32_16x16x32_bf16 v[28:31], v[156:159], v[164:167], v[28:31]
	v_mfma_f32_16x16x32_bf16 v[20:23], v[156:159], v[172:175], v[20:23]
	v_mfma_f32_16x16x32_bf16 v[24:27], v[148:151], v[172:175], v[24:27]
	v_mfma_f32_16x16x32_bf16 v[16:19], v[148:151], v[180:183], v[16:19]
	v_mfma_f32_16x16x32_bf16 v[12:15], v[156:159], v[180:183], v[12:15]
	v_mfma_f32_16x16x32_bf16 v[2:5], v[156:159], v[188:191], v[2:5]
	v_mfma_f32_16x16x32_bf16 v[6:9], v[148:151], v[188:191], v[8:11]
	v_mfma_f32_16x16x32_bf16 v[32:35], v[152:155], v[168:171], v[32:35]
	v_mfma_f32_16x16x32_bf16 v[28:31], v[160:163], v[168:171], v[28:31]
	v_mfma_f32_16x16x32_bf16 v[20:23], v[160:163], v[176:179], v[20:23]
	v_mfma_f32_16x16x32_bf16 v[24:27], v[152:155], v[176:179], v[24:27]
	v_mfma_f32_16x16x32_bf16 v[16:19], v[152:155], v[184:187], v[16:19]
	v_mfma_f32_16x16x32_bf16 v[12:15], v[160:163], v[184:187], v[12:15]
	v_mfma_f32_16x16x32_bf16 v[8:11], v[152:155], v[192:195], v[6:9]
	v_mfma_f32_16x16x32_bf16 v[4:7], v[160:163], v[192:195], v[2:5]
	s_barrier
	s_setprio 0
	s_add_i32 s38, s38, 2
	s_add_u32 s19, s19, 0x100
	s_addc_u32 s23, s23, 0
	s_cmp_gt_u32 s38, 13
	s_mov_b64 s[12:13], s[16:17]
	s_cbranch_scc0 .Ltrl_loop1

; #define PG8_STAGE(bufoff, gbase, voff) do { const int so_ = (int)(unsigned)((const char*)(gbase) - base_##voff); _Pragma("unroll") for (int _i = 0; _i < 2; ++_i) \
;         __builtin_amdgcn_raw_ptr_buffer_load_lds(rs_##voff, (PG8_LAS unsigned*)(lds + (bufoff) + ldsw + _i * 8192), 16, (int)(voff)[_i], so_, 0, 0); } while (0)
; #define PG8_LDA(dst, b, h) do { _Pragma("unroll") for (int m = 0; m < 4; ++m) _Pragma("unroll") for (int k = 0; k < 2; ++k) dst[m][k] = *(const PG8_LAS bf16x8*)(lds + PG8_SA(b, h) + aoff + m * 2048 + k * 1024); } while (0)
; #define PG8_WAIT_V(n) asm volatile("s_waitcnt vmcnt(" #n ")" ::: "memory")
; #define PG8_WAIT_L(n) asm volatile("s_waitcnt lgkmcnt(" #n ")" ::: "memory")
; template <class Epi, class Sched, bool ALIGN_EPI = false, bool SP2 = false>
; __device__ __forceinline__ void gemm_phase(PG8_LAS unsigned char* lds, const Gemm g, const Sched& S, const Epi& E, int tid_in) {
;     ...
;         for (int t = 0; t < nt; t += 2) {
;             const bool last = (t == nt - 2);
;             const char* a1 = cA + (size_t)(t + 1) * kstep;
;             const char* a2 = last ? nA : cA + (size_t)(t + 2) * kstep; const char* b2 = last ? nB : cB + (size_t)(t + 2) * kstep;
;             const char* a3 = a2 + kstep; const char* b3 = b2 + kstep;
;             if (last && has_next) S.a_ready(nxt);
;             if constexpr (SP2) {
;             PG8_LDB(B0, 0, 0); PG8_LDB(B1, 0, 1); PG8_SCHED; PG8_LDA(At, 0, 0); PG8_STAGE(PG8_SA(1, 1), a1 + hstepA, voffA);
;             PG8_WAIT_V(8); PG8_WAIT_L(0); PG8_BAR; PG8_MMA(0, 0, At, B0); PG8_MMA(0, 1, At, B1); PG8_BAR; PG8_SCHED;
;             PG8_LDA(At, 0, 1); PG8_STAGE(PG8_SB(0, 0), b2, voffB); PG8_STAGE(PG8_SB(0, 1), b2 + hstepB, voffB); PG8_STAGE(PG8_SA(0, 0), a2, voffA);
;             PG8_WAIT_V(8); PG8_WAIT_L(0); PG8_BAR; PG8_MMA(1, 0, At, B0); PG8_MMA(1, 1, At, B1); PG8_BAR; PG8_SCHED;
;             PG8_LDB(B0, 1, 0); PG8_LDB(B1, 1, 1); PG8_SCHED; PG8_LDA(At, 1, 0); PG8_STAGE(PG8_SA(0, 1), a2 + hstepA, voffA);
;             PG8_WAIT_V(8); PG8_WAIT_L(0); PG8_BAR; PG8_MMA(0, 0, At, B0); PG8_MMA(0, 1, At, B1); PG8_BAR; PG8_SCHED;
;             PG8_LDA(At, 1, 1); PG8_STAGE(PG8_SB(1, 0), b3, voffB); PG8_STAGE(PG8_SB(1, 1), b3 + hstepB, voffB); PG8_STAGE(PG8_SA(1, 0), a3, voffA);
;             PG8_WAIT_V(8); PG8_WAIT_L(0); PG8_BAR; PG8_MMA(1, 0, At, B0); PG8_MMA(1, 1, At, B1); PG8_BAR; PG8_SCHED;
.Ltrl_loop2:
	v_add_u32_e32 v133, 0x10000, v131
	ds_read_b128 v[134:137], v133
	ds_read_b128 v[138:141], v133 offset:1024
	ds_read_b128 v[142:145], v133 offset:2048
	ds_read_b128 v[146:149], v133 offset:3072
	v_add_u32_e32 v133, 0x14000, v131
	ds_read_b128 v[150:153], v133
	ds_read_b128 v[154:157], v133 offset:1024
	ds_read_b128 v[158:161], v133 offset:2048
	ds_read_b128 v[166:169], v133 offset:3072
	s_add_i32 s42, s18, s44
	s_add_i32 s21, s14, s44
	s_add_i32 s79, s12, s44
	s_addk_i32 s42, 0xff80
	s_sub_i32 vcc_lo, s42, 0x80000
	s_cmp_eq_u32 s19, 28
	s_cselect_b32 s21, s15, s21
	s_mov_b32 m0, s75
	ds_read_b128 v[170:173], v132
	ds_read_b128 v[174:177], v132 offset:1024
	ds_read_b128 v[178:181], v132 offset:2048
	ds_read_b128 v[182:185], v132 offset:3072
	ds_read_b128 v[186:189], v132 offset:4096
	ds_read_b128 v[190:193], v132 offset:5120
	ds_read_b128 v[200:203], v132 offset:6144
	ds_read_b128 v[206:209], v132 offset:7168
	s_mov_b32 m0, s72
	s_nop 0
	buffer_load_dwordx4 v130, s[4:7], vcc_lo offen lds
	s_mov_b32 m0, s75
	s_nop 0
	buffer_load_dwordx4 v0, s[4:7], s42 offen lds
	s_mov_b32 m0, s76
	s_nop 0
	buffer_load_dwordx4 v130, s[4:7], s42 offen lds
	s_waitcnt vmcnt(8)
	s_waitcnt lgkmcnt(0)
	s_setprio 1
	s_barrier
	v_mfma_f32_16x16x32_bf16 v[34:37], v[134:137], v[170:173], v[34:37]
	v_mfma_f32_16x16x32_bf16 v[18:21], v[142:145], v[170:173], v[18:21]
	v_mfma_f32_16x16x32_bf16 v[78:81], v[142:145], v[178:181], v[78:81]
	v_mfma_f32_16x16x32_bf16 v[86:89], v[134:137], v[178:181], v[86:89]
	v_mfma_f32_16x16x32_bf16 v[106:109], v[134:137], v[186:189], v[106:109]
	v_mfma_f32_16x16x32_bf16 v[102:105], v[142:145], v[186:189], v[102:105]
	v_mfma_f32_16x16x32_bf16 v[122:125], v[142:145], v[200:203], v[122:125]
	v_mfma_f32_16x16x32_bf16 v[126:129], v[134:137], v[200:203], v[126:129]
	v_mfma_f32_16x16x32_bf16 v[34:37], v[138:141], v[174:177], v[34:37]
	v_mfma_f32_16x16x32_bf16 v[18:21], v[146:149], v[174:177], v[18:21]
	v_mfma_f32_16x16x32_bf16 v[78:81], v[146:149], v[182:185], v[78:81]
	v_mfma_f32_16x16x32_bf16 v[86:89], v[138:141], v[182:185], v[86:89]
	v_mfma_f32_16x16x32_bf16 v[106:109], v[138:141], v[190:193], v[106:109]
	v_mfma_f32_16x16x32_bf16 v[102:105], v[146:149], v[190:193], v[102:105]
	v_mfma_f32_16x16x32_bf16 v[122:125], v[146:149], v[206:209], v[122:125]
	v_mfma_f32_16x16x32_bf16 v[126:129], v[138:141], v[206:209], v[126:129]
	v_mfma_f32_16x16x32_bf16 v[14:17], v[150:153], v[170:173], v[14:17]
	v_mfma_f32_16x16x32_bf16 v[38:41], v[158:161], v[170:173], v[38:41]
	ds_read_b128 v[170:173], v132 offset:16384
	v_mfma_f32_16x16x32_bf16 v[90:93], v[158:161], v[178:181], v[90:93]
	v_mfma_f32_16x16x32_bf16 v[74:77], v[150:153], v[178:181], v[74:77]
	ds_read_b128 v[178:181], v132 offset:18432
	v_mfma_f32_16x16x32_bf16 v[98:101], v[150:153], v[186:189], v[98:101]
	v_mfma_f32_16x16x32_bf16 v[110:113], v[158:161], v[186:189], v[110:113]
	ds_read_b128 v[186:189], v132 offset:20480
	v_mfma_f32_16x16x32_bf16 v[114:117], v[158:161], v[200:203], v[114:117]
	v_mfma_f32_16x16x32_bf16 v[118:121], v[150:153], v[200:203], v[118:121]
	ds_read_b128 v[200:203], v132 offset:22528
	v_mfma_f32_16x16x32_bf16 v[14:17], v[154:157], v[174:177], v[14:17]
	v_mfma_f32_16x16x32_bf16 v[38:41], v[166:169], v[174:177], v[38:41]
	ds_read_b128 v[174:177], v132 offset:17408
	v_mfma_f32_16x16x32_bf16 v[90:93], v[166:169], v[182:185], v[90:93]
	v_mfma_f32_16x16x32_bf16 v[74:77], v[154:157], v[182:185], v[74:77]
	ds_read_b128 v[182:185], v132 offset:19456
	v_mfma_f32_16x16x32_bf16 v[98:101], v[154:157], v[190:193], v[98:101]
	v_mfma_f32_16x16x32_bf16 v[110:113], v[166:169], v[190:193], v[110:113]
	ds_read_b128 v[190:193], v132 offset:21504
	v_mfma_f32_16x16x32_bf16 v[114:117], v[166:169], v[206:209], v[114:117]
	v_mfma_f32_16x16x32_bf16 v[118:121], v[154:157], v[206:209], v[118:121]
	ds_read_b128 v[206:209], v132 offset:23552
	s_barrier
	s_setprio 0
	s_cselect_b32 s79, s17, s79
	s_mov_b32 m0, s49
	s_mov_b32 s42, s6
	s_mov_b32 s43, s7
	s_sub_i32 s79, s79, s40
	buffer_load_dwordx4 v0, s[40:43], s79 offen lds
	s_mov_b32 m0, s60
	s_add_i32 vcc_lo, s79, 0x80000
	buffer_load_dwordx4 v130, s[40:43], s79 offen lds
	s_mov_b32 m0, s61
	s_sub_i32 s21, s21, s4
	buffer_load_dwordx4 v0, s[40:43], vcc_lo offen lds
	s_mov_b32 m0, s62
	s_nop 0
	buffer_load_dwordx4 v130, s[40:43], vcc_lo offen lds
	s_mov_b32 m0, s35
	s_nop 0
	buffer_load_dwordx4 v0, s[4:7], s21 offen lds
	s_waitcnt vmcnt(7)
	s_waitcnt lgkmcnt(0)
	s_setprio 1
	s_barrier
	v_mfma_f32_16x16x32_bf16 v[50:53], v[134:137], v[170:173], v[50:53]
	v_mfma_f32_16x16x32_bf16 v[30:33], v[142:145], v[170:173], v[30:33]
	v_mfma_f32_16x16x32_bf16 v[58:61], v[142:145], v[178:181], v[58:61]
	v_mfma_f32_16x16x32_bf16 v[62:65], v[134:137], v[178:181], v[62:65]
	v_mfma_f32_16x16x32_bf16 v[94:97], v[134:137], v[186:189], v[94:97]
	v_mfma_f32_16x16x32_bf16 v[82:85], v[142:145], v[186:189], v[82:85]
	v_mfma_f32_16x16x32_bf16 v[26:29], v[142:145], v[200:203], v[26:29]
	v_mfma_f32_16x16x32_bf16 v[46:49], v[134:137], v[200:203], v[46:49]
	v_mfma_f32_16x16x32_bf16 v[50:53], v[138:141], v[174:177], v[50:53]
	v_mfma_f32_16x16x32_bf16 v[30:33], v[146:149], v[174:177], v[30:33]
	v_mfma_f32_16x16x32_bf16 v[58:61], v[146:149], v[182:185], v[58:61]
	v_mfma_f32_16x16x32_bf16 v[62:65], v[138:141], v[182:185], v[62:65]
	v_mfma_f32_16x16x32_bf16 v[94:97], v[138:141], v[190:193], v[94:97]
	v_mfma_f32_16x16x32_bf16 v[82:85], v[146:149], v[190:193], v[82:85]
	v_mfma_f32_16x16x32_bf16 v[26:29], v[146:149], v[206:209], v[26:29]
	v_mfma_f32_16x16x32_bf16 v[46:49], v[138:141], v[206:209], v[46:49]
	v_mfma_f32_16x16x32_bf16 v[22:25], v[150:153], v[170:173], v[22:25]
	v_mfma_f32_16x16x32_bf16 v[10:13], v[158:161], v[170:173], v[10:13]
	v_mfma_f32_16x16x32_bf16 v[66:69], v[158:161], v[178:181], v[66:69]
	v_mfma_f32_16x16x32_bf16 v[54:57], v[150:153], v[178:181], v[54:57]
	v_mfma_f32_16x16x32_bf16 v[70:73], v[150:153], v[186:189], v[70:73]
	v_mfma_f32_16x16x32_bf16 v[42:45], v[158:161], v[186:189], v[42:45]
	v_mfma_f32_16x16x32_bf16 v[2:5], v[158:161], v[200:203], v[2:5]
	v_mfma_f32_16x16x32_bf16 v[6:9], v[150:153], v[200:203], v[6:9]
	v_mfma_f32_16x16x32_bf16 v[22:25], v[154:157], v[174:177], v[22:25]
	v_mfma_f32_16x16x32_bf16 v[10:13], v[166:169], v[174:177], v[10:13]
	v_mfma_f32_16x16x32_bf16 v[66:69], v[166:169], v[182:185], v[66:69]
	v_mfma_f32_16x16x32_bf16 v[54:57], v[154:157], v[182:185], v[54:57]
	v_mfma_f32_16x16x32_bf16 v[70:73], v[154:157], v[190:193], v[70:73]
	v_mfma_f32_16x16x32_bf16 v[42:45], v[166:169], v[190:193], v[42:45]
	v_mfma_f32_16x16x32_bf16 v[2:5], v[166:169], v[206:209], v[2:5]
	v_mfma_f32_16x16x32_bf16 v[6:9], v[154:157], v[206:209], v[6:9]
	s_barrier
; #define PG8_STAGE(bufoff, gbase, voff) do { const int so_ = (int)(unsigned)((const char*)(gbase) - base_##voff); _Pragma("unroll") for (int _i = 0; _i < 2; ++_i) \
;         __builtin_amdgcn_raw_ptr_buffer_load_lds(rs_##voff, (PG8_LAS unsigned*)(lds + (bufoff) + ldsw + _i * 8192), 16, (int)(voff)[_i], so_, 0, 0); } while (0)
; #define PG8_LDA(dst, b, h) do { _Pragma("unroll") for (int m = 0; m < 4; ++m) _Pragma("unroll") for (int k = 0; k < 2; ++k) dst[m][k] = *(const PG8_LAS bf16x8*)(lds + PG8_SA(b, h) + aoff + m * 2048 + k * 1024); } while (0)
; #define PG8_WAIT_V(n) asm volatile("s_waitcnt vmcnt(" #n ")" ::: "memory")
; #define PG8_WAIT_L(n) asm volatile("s_waitcnt lgkmcnt(" #n ")" ::: "memory")
; template <class Epi, class Sched, bool ALIGN_EPI = false, bool SP2 = false>
; __device__ __forceinline__ void gemm_phase(PG8_LAS unsigned char* lds, const Gemm g, const Sched& S, const Epi& E, int tid_in) {
;     ...
;         for (int t = 0; t < nt; t += 2) {
;             const bool last = (t == nt - 2);
;             const char* a1 = cA + (size_t)(t + 1) * kstep;
;             const char* a2 = last ? nA : cA + (size_t)(t + 2) * kstep; const char* b2 = last ? nB : cB + (size_t)(t + 2) * kstep;
;             const char* a3 = a2 + kstep; const char* b3 = b2 + kstep;
;             if (last && has_next) S.a_ready(nxt);
;             if constexpr (SP2) {
;             PG8_LDB(B0, 0, 0); PG8_LDB(B1, 0, 1); PG8_SCHED; PG8_LDA(At, 0, 0); PG8_STAGE(PG8_SA(1, 1), a1 + hstepA, voffA);
;             PG8_WAIT_V(8); PG8_WAIT_L(0); PG8_BAR; PG8_MMA(0, 0, At, B0); PG8_MMA(0, 1, At, B1); PG8_BAR; PG8_SCHED;
;             PG8_LDA(At, 0, 1); PG8_STAGE(PG8_SB(0, 0), b2, voffB); PG8_STAGE(PG8_SB(0, 1), b2 + hstepB, voffB); PG8_STAGE(PG8_SA(0, 0), a2, voffA);
;             PG8_WAIT_V(8); PG8_WAIT_L(0); PG8_BAR; PG8_MMA(1, 0, At, B0); PG8_MMA(1, 1, At, B1); PG8_BAR; PG8_SCHED;
;             PG8_LDB(B0, 1, 0); PG8_LDB(B1, 1, 1); PG8_SCHED; PG8_LDA(At, 1, 0); PG8_STAGE(PG8_SA(0, 1), a2 + hstepA, voffA);
;             PG8_WAIT_V(8); PG8_WAIT_L(0); PG8_BAR; PG8_MMA(0, 0, At, B0); PG8_MMA(0, 1, At, B1); PG8_BAR; PG8_SCHED;
;             PG8_LDA(At, 1, 1); PG8_STAGE(PG8_SB(1, 0), b3, voffB); PG8_STAGE(PG8_SB(1, 1), b3 + hstepB, voffB); PG8_STAGE(PG8_SA(1, 0), a3, voffA);
;             PG8_WAIT_V(8); PG8_WAIT_L(0); PG8_BAR; PG8_MMA(1, 0, At, B0); PG8_MMA(1, 1, At, B1); PG8_BAR; PG8_SCHED;
	s_setprio 0
	v_add_u32_e32 v133, 0x18000, v131
	ds_read_b128 v[134:137], v133
	ds_read_b128 v[138:141], v133 offset:1024
	ds_read_b128 v[142:145], v133 offset:2048
	ds_read_b128 v[146:149], v133 offset:3072
	v_add_u32_e32 v133, 0x1c000, v131
	ds_read_b128 v[150:153], v133
	ds_read_b128 v[154:157], v133 offset:1024
	ds_read_b128 v[158:161], v133 offset:2048
	ds_read_b128 v[166:169], v133 offset:3072
	s_add_i32 vcc_lo, s21, 0x80000
	s_mov_b32 m0, s66
	ds_read_b128 v[170:173], v132 offset:32768
	ds_read_b128 v[174:177], v132 offset:33792
	ds_read_b128 v[178:181], v132 offset:34816
	ds_read_b128 v[182:185], v132 offset:35840
	ds_read_b128 v[186:189], v132 offset:36864
	ds_read_b128 v[190:193], v132 offset:37888
	ds_read_b128 v[200:203], v132 offset:38912
	ds_read_b128 v[206:209], v132 offset:39936
	s_mov_b32 m0, s63
	s_nop 0
	buffer_load_dwordx4 v130, s[4:7], s21 offen lds
	s_mov_b32 m0, s66
	s_nop 0
	buffer_load_dwordx4 v0, s[4:7], vcc_lo offen lds
	s_mov_b32 m0, s67
	s_nop 0
	buffer_load_dwordx4 v130, s[4:7], vcc_lo offen lds
	s_waitcnt vmcnt(8)
	s_waitcnt lgkmcnt(0)
	s_setprio 1
	s_barrier
	v_mfma_f32_16x16x32_bf16 v[34:37], v[134:137], v[170:173], v[34:37]
	v_mfma_f32_16x16x32_bf16 v[18:21], v[142:145], v[170:173], v[18:21]
	v_mfma_f32_16x16x32_bf16 v[78:81], v[142:145], v[178:181], v[78:81]
	v_mfma_f32_16x16x32_bf16 v[86:89], v[134:137], v[178:181], v[86:89]
	v_mfma_f32_16x16x32_bf16 v[106:109], v[134:137], v[186:189], v[106:109]
	v_mfma_f32_16x16x32_bf16 v[102:105], v[142:145], v[186:189], v[102:105]
	v_mfma_f32_16x16x32_bf16 v[122:125], v[142:145], v[200:203], v[122:125]
	v_mfma_f32_16x16x32_bf16 v[126:129], v[134:137], v[200:203], v[126:129]
	v_mfma_f32_16x16x32_bf16 v[34:37], v[138:141], v[174:177], v[34:37]
	v_mfma_f32_16x16x32_bf16 v[18:21], v[146:149], v[174:177], v[18:21]
	v_mfma_f32_16x16x32_bf16 v[78:81], v[146:149], v[182:185], v[78:81]
	v_mfma_f32_16x16x32_bf16 v[86:89], v[138:141], v[182:185], v[86:89]
	v_mfma_f32_16x16x32_bf16 v[106:109], v[138:141], v[190:193], v[106:109]
	v_mfma_f32_16x16x32_bf16 v[102:105], v[146:149], v[190:193], v[102:105]
	v_mfma_f32_16x16x32_bf16 v[122:125], v[146:149], v[206:209], v[122:125]
	v_mfma_f32_16x16x32_bf16 v[126:129], v[138:141], v[206:209], v[126:129]
	v_mfma_f32_16x16x32_bf16 v[14:17], v[150:153], v[170:173], v[14:17]
	v_mfma_f32_16x16x32_bf16 v[38:41], v[158:161], v[170:173], v[38:41]
	ds_read_b128 v[170:173], v132 offset:49152
	v_mfma_f32_16x16x32_bf16 v[90:93], v[158:161], v[178:181], v[90:93]
	v_mfma_f32_16x16x32_bf16 v[74:77], v[150:153], v[178:181], v[74:77]
	ds_read_b128 v[178:181], v132 offset:51200
	v_mfma_f32_16x16x32_bf16 v[98:101], v[150:153], v[186:189], v[98:101]
	v_mfma_f32_16x16x32_bf16 v[110:113], v[158:161], v[186:189], v[110:113]
	ds_read_b128 v[186:189], v132 offset:53248
	v_mfma_f32_16x16x32_bf16 v[114:117], v[158:161], v[200:203], v[114:117]
	v_mfma_f32_16x16x32_bf16 v[118:121], v[150:153], v[200:203], v[118:121]
	ds_read_b128 v[200:203], v132 offset:55296
	v_mfma_f32_16x16x32_bf16 v[14:17], v[154:157], v[174:177], v[14:17]
	v_mfma_f32_16x16x32_bf16 v[38:41], v[166:169], v[174:177], v[38:41]
	ds_read_b128 v[174:177], v132 offset:50176
	v_mfma_f32_16x16x32_bf16 v[90:93], v[166:169], v[182:185], v[90:93]
	v_mfma_f32_16x16x32_bf16 v[74:77], v[154:157], v[182:185], v[74:77]
	ds_read_b128 v[182:185], v132 offset:52224
	v_mfma_f32_16x16x32_bf16 v[98:101], v[154:157], v[190:193], v[98:101]
	v_mfma_f32_16x16x32_bf16 v[110:113], v[166:169], v[190:193], v[110:113]
	ds_read_b128 v[190:193], v132 offset:54272
	v_mfma_f32_16x16x32_bf16 v[114:117], v[166:169], v[206:209], v[114:117]
	v_mfma_f32_16x16x32_bf16 v[118:121], v[154:157], v[206:209], v[118:121]
	ds_read_b128 v[206:209], v132 offset:56320
	s_barrier
	s_setprio 0
	s_mov_b32 m0, s68
	s_add_i32 vcc_lo, s79, 0x80
	buffer_load_dwordx4 v0, s[40:43], vcc_lo offen lds
	s_mov_b32 m0, s69
	s_add_i32 s79, s79, 0x80080
	buffer_load_dwordx4 v130, s[40:43], vcc_lo offen lds
	s_mov_b32 m0, s73
	s_addk_i32 s21, 0x80
	buffer_load_dwordx4 v0, s[40:43], s79 offen lds
	s_mov_b32 m0, s74
	s_nop 0
	buffer_load_dwordx4 v130, s[40:43], s79 offen lds
	s_mov_b32 m0, s71
	s_nop 0
	buffer_load_dwordx4 v0, s[4:7], s21 offen lds
	s_waitcnt vmcnt(7)
	s_waitcnt lgkmcnt(0)
	s_setprio 1
	s_barrier
	v_mfma_f32_16x16x32_bf16 v[50:53], v[134:137], v[170:173], v[50:53]
	v_mfma_f32_16x16x32_bf16 v[30:33], v[142:145], v[170:173], v[30:33]
	v_mfma_f32_16x16x32_bf16 v[58:61], v[142:145], v[178:181], v[58:61]
	v_mfma_f32_16x16x32_bf16 v[62:65], v[134:137], v[178:181], v[62:65]
	v_mfma_f32_16x16x32_bf16 v[94:97], v[134:137], v[186:189], v[94:97]
	v_mfma_f32_16x16x32_bf16 v[82:85], v[142:145], v[186:189], v[82:85]
	v_mfma_f32_16x16x32_bf16 v[26:29], v[142:145], v[200:203], v[26:29]
	v_mfma_f32_16x16x32_bf16 v[46:49], v[134:137], v[200:203], v[46:49]
	v_mfma_f32_16x16x32_bf16 v[50:53], v[138:141], v[174:177], v[50:53]
	v_mfma_f32_16x16x32_bf16 v[30:33], v[146:149], v[174:177], v[30:33]
	v_mfma_f32_16x16x32_bf16 v[58:61], v[146:149], v[182:185], v[58:61]
	v_mfma_f32_16x16x32_bf16 v[62:65], v[138:141], v[182:185], v[62:65]
	v_mfma_f32_16x16x32_bf16 v[94:97], v[138:141], v[190:193], v[94:97]
	v_mfma_f32_16x16x32_bf16 v[82:85], v[146:149], v[190:193], v[82:85]
	v_mfma_f32_16x16x32_bf16 v[26:29], v[146:149], v[206:209], v[26:29]
	v_mfma_f32_16x16x32_bf16 v[46:49], v[138:141], v[206:209], v[46:49]
	v_mfma_f32_16x16x32_bf16 v[22:25], v[150:153], v[170:173], v[22:25]
	v_mfma_f32_16x16x32_bf16 v[10:13], v[158:161], v[170:173], v[10:13]
	v_mfma_f32_16x16x32_bf16 v[66:69], v[158:161], v[178:181], v[66:69]
	v_mfma_f32_16x16x32_bf16 v[54:57], v[150:153], v[178:181], v[54:57]
	v_mfma_f32_16x16x32_bf16 v[70:73], v[150:153], v[186:189], v[70:73]
	v_mfma_f32_16x16x32_bf16 v[42:45], v[158:161], v[186:189], v[42:45]
	v_mfma_f32_16x16x32_bf16 v[2:5], v[158:161], v[200:203], v[2:5]
	v_mfma_f32_16x16x32_bf16 v[6:9], v[150:153], v[200:203], v[6:9]
	v_mfma_f32_16x16x32_bf16 v[22:25], v[154:157], v[174:177], v[22:25]
	v_mfma_f32_16x16x32_bf16 v[10:13], v[166:169], v[174:177], v[10:13]
	v_mfma_f32_16x16x32_bf16 v[66:69], v[166:169], v[182:185], v[66:69]
	v_mfma_f32_16x16x32_bf16 v[54:57], v[154:157], v[182:185], v[54:57]
	v_mfma_f32_16x16x32_bf16 v[70:73], v[154:157], v[190:193], v[70:73]
	v_mfma_f32_16x16x32_bf16 v[42:45], v[166:169], v[190:193], v[42:45]
	v_mfma_f32_16x16x32_bf16 v[2:5], v[166:169], v[206:209], v[2:5]
	v_mfma_f32_16x16x32_bf16 v[6:9], v[154:157], v[206:209], v[6:9]
	s_barrier
	s_setprio 0
	s_add_i32 s19, s19, 2
	s_add_u32 s44, s44, 0x100
	s_addc_u32 s45, s45, 0
	s_cmp_gt_u32 s19, 29
	s_cbranch_scc0 .Ltrl_loop2

; #define PG8_STAGE(bufoff, gbase, voff) do { const int so_ = (int)(unsigned)((const char*)(gbase) - base_##voff); _Pragma("unroll") for (int _i = 0; _i < 2; ++_i) \
;         __builtin_amdgcn_raw_ptr_buffer_load_lds(rs_##voff, (PG8_LAS unsigned*)(lds + (bufoff) + ldsw + _i * 8192), 16, (int)(voff)[_i], so_, 0, 0); } while (0)
; #define PG8_LDA(dst, b, h) do { _Pragma("unroll") for (int m = 0; m < 4; ++m) _Pragma("unroll") for (int k = 0; k < 2; ++k) dst[m][k] = *(const PG8_LAS bf16x8*)(lds + PG8_SA(b, h) + aoff + m * 2048 + k * 1024); } while (0)
; #define PG8_WAIT_V(n) asm volatile("s_waitcnt vmcnt(" #n ")" ::: "memory")
; #define PG8_WAIT_L(n) asm volatile("s_waitcnt lgkmcnt(" #n ")" ::: "memory")
; template <class Epi, class Sched, bool ALIGN_EPI = false, bool SP2 = false>
; __device__ __forceinline__ void gemm_phase(PG8_LAS unsigned char* lds, const Gemm g, const Sched& S, const Epi& E, int tid_in) {
;     ...
;         for (int t = 0; t < nt; t += 2) {
;             const bool last = (t == nt - 2);
;             const char* a1 = cA + (size_t)(t + 1) * kstep;
;             const char* a2 = last ? nA : cA + (size_t)(t + 2) * kstep; const char* b2 = last ? nB : cB + (size_t)(t + 2) * kstep;
;             const char* a3 = a2 + kstep; const char* b3 = b2 + kstep;
;             if (last && has_next) S.a_ready(nxt);
;             if constexpr (SP2) {
;             PG8_LDB(B0, 0, 0); PG8_LDB(B1, 0, 1); PG8_SCHED; PG8_LDA(At, 0, 0); PG8_STAGE(PG8_SA(1, 1), a1 + hstepA, voffA);
;             PG8_WAIT_V(8); PG8_WAIT_L(0); PG8_BAR; PG8_MMA(0, 0, At, B0); PG8_MMA(0, 1, At, B1); PG8_BAR; PG8_SCHED;
;             PG8_LDA(At, 0, 1); PG8_STAGE(PG8_SB(0, 0), b2, voffB); PG8_STAGE(PG8_SB(0, 1), b2 + hstepB, voffB); PG8_STAGE(PG8_SA(0, 0), a2, voffA);
;             PG8_WAIT_V(8); PG8_WAIT_L(0); PG8_BAR; PG8_MMA(1, 0, At, B0); PG8_MMA(1, 1, At, B1); PG8_BAR; PG8_SCHED;
;             PG8_LDB(B0, 1, 0); PG8_LDB(B1, 1, 1); PG8_SCHED; PG8_LDA(At, 1, 0); PG8_STAGE(PG8_SA(0, 1), a2 + hstepA, voffA);
;             PG8_WAIT_V(8); PG8_WAIT_L(0); PG8_BAR; PG8_MMA(0, 0, At, B0); PG8_MMA(0, 1, At, B1); PG8_BAR; PG8_SCHED;
;             PG8_LDA(At, 1, 1); PG8_STAGE(PG8_SB(1, 0), b3, voffB); PG8_STAGE(PG8_SB(1, 1), b3 + hstepB, voffB); PG8_STAGE(PG8_SA(1, 0), a3, voffA);
;             PG8_WAIT_V(8); PG8_WAIT_L(0); PG8_BAR; PG8_MMA(1, 0, At, B0); PG8_MMA(1, 1, At, B1); PG8_BAR; PG8_SCHED;
.Ltrl_loop3:
	v_add_u32_e32 v141, 0x10000, v139
	ds_read_b128 v[130:133], v141
	ds_read_b128 v[142:145], v141 offset:1024
	ds_read_b128 v[146:149], v141 offset:2048
	ds_read_b128 v[150:153], v141 offset:3072
	v_add_u32_e32 v141, 0x14000, v139
	ds_read_b128 v[154:157], v141
	ds_read_b128 v[158:161], v141 offset:1024
	ds_read_b128 v[162:165], v141 offset:2048
	ds_read_b128 v[166:169], v141 offset:3072
	s_add_u32 s38, s16, 0x100
	s_addc_u32 s39, s17, 0
	s_sub_i32 s16, s16, s4
	s_add_i32 s16, s16, 0x80080
	s_sub_i32 s74, s16, 0x80000
	s_cmp_eq_u32 s73, 28
	s_cselect_b32 s17, s18, s38
	s_mov_b32 m0, s67
	ds_read_b128 v[170:173], v140
	ds_read_b128 v[174:177], v140 offset:1024
	ds_read_b128 v[178:181], v140 offset:2048
	ds_read_b128 v[182:185], v140 offset:3072
	ds_read_b128 v[186:189], v140 offset:4096
	ds_read_b128 v[190:193], v140 offset:5120
	ds_read_b128 v[200:203], v140 offset:6144
	ds_read_b128 v[206:209], v140 offset:7168
	s_mov_b32 m0, s62
	s_nop 0
	buffer_load_dwordx4 v135, s[4:7], s74 offen lds
	s_mov_b32 m0, s67
	s_nop 0
	buffer_load_dwordx4 v0, s[4:7], s16 offen lds
	s_mov_b32 m0, s68
	s_nop 0
	buffer_load_dwordx4 v135, s[4:7], s16 offen lds
	s_waitcnt vmcnt(8)
	s_waitcnt lgkmcnt(0)
	s_setprio 1
	s_barrier
	v_mfma_f32_16x16x32_bf16 v[126:129], v[130:133], v[170:173], v[126:129]
	v_mfma_f32_16x16x32_bf16 v[122:125], v[146:149], v[170:173], v[122:125]
	v_mfma_f32_16x16x32_bf16 v[106:109], v[146:149], v[178:181], v[106:109]
	v_mfma_f32_16x16x32_bf16 v[110:113], v[130:133], v[178:181], v[110:113]
	v_mfma_f32_16x16x32_bf16 v[94:97], v[130:133], v[186:189], v[94:97]
	v_mfma_f32_16x16x32_bf16 v[90:93], v[146:149], v[186:189], v[90:93]
	v_mfma_f32_16x16x32_bf16 v[74:77], v[146:149], v[200:203], v[74:77]
	v_mfma_f32_16x16x32_bf16 v[78:81], v[130:133], v[200:203], v[78:81]
	v_mfma_f32_16x16x32_bf16 v[126:129], v[142:145], v[174:177], v[126:129]
	v_mfma_f32_16x16x32_bf16 v[122:125], v[150:153], v[174:177], v[122:125]
	v_mfma_f32_16x16x32_bf16 v[106:109], v[150:153], v[182:185], v[106:109]
	v_mfma_f32_16x16x32_bf16 v[110:113], v[142:145], v[182:185], v[110:113]
	v_mfma_f32_16x16x32_bf16 v[94:97], v[142:145], v[190:193], v[94:97]
	v_mfma_f32_16x16x32_bf16 v[90:93], v[150:153], v[190:193], v[90:93]
	v_mfma_f32_16x16x32_bf16 v[74:77], v[150:153], v[206:209], v[74:77]
	v_mfma_f32_16x16x32_bf16 v[78:81], v[142:145], v[206:209], v[78:81]
	v_mfma_f32_16x16x32_bf16 v[118:121], v[154:157], v[170:173], v[118:121]
	v_mfma_f32_16x16x32_bf16 v[114:117], v[162:165], v[170:173], v[114:117]
	ds_read_b128 v[170:173], v140 offset:16384
	v_mfma_f32_16x16x32_bf16 v[98:101], v[162:165], v[178:181], v[98:101]
	v_mfma_f32_16x16x32_bf16 v[102:105], v[154:157], v[178:181], v[102:105]
	ds_read_b128 v[178:181], v140 offset:18432
	v_mfma_f32_16x16x32_bf16 v[86:89], v[154:157], v[186:189], v[86:89]
	v_mfma_f32_16x16x32_bf16 v[82:85], v[162:165], v[186:189], v[82:85]
	ds_read_b128 v[186:189], v140 offset:20480
	v_mfma_f32_16x16x32_bf16 v[66:69], v[162:165], v[200:203], v[66:69]
	v_mfma_f32_16x16x32_bf16 v[70:73], v[154:157], v[200:203], v[70:73]
	ds_read_b128 v[200:203], v140 offset:22528
	v_mfma_f32_16x16x32_bf16 v[118:121], v[158:161], v[174:177], v[118:121]
	v_mfma_f32_16x16x32_bf16 v[114:117], v[166:169], v[174:177], v[114:117]
	ds_read_b128 v[174:177], v140 offset:17408
	v_mfma_f32_16x16x32_bf16 v[98:101], v[166:169], v[182:185], v[98:101]
	v_mfma_f32_16x16x32_bf16 v[102:105], v[158:161], v[182:185], v[102:105]
	ds_read_b128 v[182:185], v140 offset:19456
	v_mfma_f32_16x16x32_bf16 v[86:89], v[158:161], v[190:193], v[86:89]
	v_mfma_f32_16x16x32_bf16 v[82:85], v[166:169], v[190:193], v[82:85]
	ds_read_b128 v[190:193], v140 offset:21504
	v_mfma_f32_16x16x32_bf16 v[66:69], v[166:169], v[206:209], v[66:69]
	v_mfma_f32_16x16x32_bf16 v[70:73], v[158:161], v[206:209], v[70:73]
	ds_read_b128 v[206:209], v140 offset:23552
	s_barrier
	s_setprio 0
	s_cselect_b32 s16, s15, s19
	s_mov_b32 m0, s35
	s_mov_b32 s42, s6
	s_mov_b32 s43, s7
	s_sub_i32 s16, s16, s40
	buffer_load_dwordx4 v134, s[40:43], s16 offen lds
	s_mov_b32 m0, s44
	s_add_i32 s74, s16, 0x80000
	buffer_load_dwordx4 v136, s[40:43], s16 offen lds
	s_mov_b32 m0, s45
	s_sub_i32 s17, s17, s4
	buffer_load_dwordx4 v134, s[40:43], s74 offen lds
	s_mov_b32 m0, s46
	s_nop 0
	buffer_load_dwordx4 v136, s[40:43], s74 offen lds
	s_mov_b32 m0, s34
	s_nop 0
	buffer_load_dwordx4 v0, s[4:7], s17 offen lds
	s_waitcnt vmcnt(7)
	s_waitcnt lgkmcnt(0)
	s_setprio 1
	s_barrier
	v_mfma_f32_16x16x32_bf16 v[62:65], v[130:133], v[170:173], v[62:65]
	v_mfma_f32_16x16x32_bf16 v[58:61], v[146:149], v[170:173], v[58:61]
	v_mfma_f32_16x16x32_bf16 v[42:45], v[146:149], v[178:181], v[42:45]
	v_mfma_f32_16x16x32_bf16 v[46:49], v[130:133], v[178:181], v[46:49]
	v_mfma_f32_16x16x32_bf16 v[30:33], v[130:133], v[186:189], v[30:33]
	v_mfma_f32_16x16x32_bf16 v[26:29], v[146:149], v[186:189], v[26:29]
	v_mfma_f32_16x16x32_bf16 v[10:13], v[146:149], v[200:203], v[10:13]
	v_mfma_f32_16x16x32_bf16 v[14:17], v[130:133], v[200:203], v[14:17]
	v_mfma_f32_16x16x32_bf16 v[62:65], v[142:145], v[174:177], v[62:65]
	v_mfma_f32_16x16x32_bf16 v[58:61], v[150:153], v[174:177], v[58:61]
	v_mfma_f32_16x16x32_bf16 v[42:45], v[150:153], v[182:185], v[42:45]
	v_mfma_f32_16x16x32_bf16 v[46:49], v[142:145], v[182:185], v[46:49]
	v_mfma_f32_16x16x32_bf16 v[30:33], v[142:145], v[190:193], v[30:33]
	v_mfma_f32_16x16x32_bf16 v[26:29], v[150:153], v[190:193], v[26:29]
	v_mfma_f32_16x16x32_bf16 v[10:13], v[150:153], v[206:209], v[10:13]
	v_mfma_f32_16x16x32_bf16 v[14:17], v[142:145], v[206:209], v[14:17]
	v_mfma_f32_16x16x32_bf16 v[54:57], v[154:157], v[170:173], v[54:57]
	v_mfma_f32_16x16x32_bf16 v[50:53], v[162:165], v[170:173], v[50:53]
	v_mfma_f32_16x16x32_bf16 v[34:37], v[162:165], v[178:181], v[34:37]
	v_mfma_f32_16x16x32_bf16 v[38:41], v[154:157], v[178:181], v[38:41]
	v_mfma_f32_16x16x32_bf16 v[22:25], v[154:157], v[186:189], v[22:25]
	v_mfma_f32_16x16x32_bf16 v[18:21], v[162:165], v[186:189], v[18:21]
	v_mfma_f32_16x16x32_bf16 v[2:5], v[162:165], v[200:203], v[2:5]
	v_mfma_f32_16x16x32_bf16 v[6:9], v[154:157], v[200:203], v[6:9]
	v_mfma_f32_16x16x32_bf16 v[54:57], v[158:161], v[174:177], v[54:57]
	v_mfma_f32_16x16x32_bf16 v[50:53], v[166:169], v[174:177], v[50:53]
	v_mfma_f32_16x16x32_bf16 v[34:37], v[166:169], v[182:185], v[34:37]
	v_mfma_f32_16x16x32_bf16 v[38:41], v[158:161], v[182:185], v[38:41]
	v_mfma_f32_16x16x32_bf16 v[22:25], v[158:161], v[190:193], v[22:25]
	v_mfma_f32_16x16x32_bf16 v[18:21], v[166:169], v[190:193], v[18:21]
	v_mfma_f32_16x16x32_bf16 v[2:5], v[166:169], v[206:209], v[2:5]
	v_mfma_f32_16x16x32_bf16 v[6:9], v[158:161], v[206:209], v[6:9]
	s_barrier
; #define PG8_STAGE(bufoff, gbase, voff) do { const int so_ = (int)(unsigned)((const char*)(gbase) - base_##voff); _Pragma("unroll") for (int _i = 0; _i < 2; ++_i) \
;         __builtin_amdgcn_raw_ptr_buffer_load_lds(rs_##voff, (PG8_LAS unsigned*)(lds + (bufoff) + ldsw + _i * 8192), 16, (int)(voff)[_i], so_, 0, 0); } while (0)
; #define PG8_LDA(dst, b, h) do { _Pragma("unroll") for (int m = 0; m < 4; ++m) _Pragma("unroll") for (int k = 0; k < 2; ++k) dst[m][k] = *(const PG8_LAS bf16x8*)(lds + PG8_SA(b, h) + aoff + m * 2048 + k * 1024); } while (0)
; #define PG8_WAIT_V(n) asm volatile("s_waitcnt vmcnt(" #n ")" ::: "memory")
; #define PG8_WAIT_L(n) asm volatile("s_waitcnt lgkmcnt(" #n ")" ::: "memory")
; template <class Epi, class Sched, bool ALIGN_EPI = false, bool SP2 = false>
; __device__ __forceinline__ void gemm_phase(PG8_LAS unsigned char* lds, const Gemm g, const Sched& S, const Epi& E, int tid_in) {
;     ...
;         for (int t = 0; t < nt; t += 2) {
;             const bool last = (t == nt - 2);
;             const char* a1 = cA + (size_t)(t + 1) * kstep;
;             const char* a2 = last ? nA : cA + (size_t)(t + 2) * kstep; const char* b2 = last ? nB : cB + (size_t)(t + 2) * kstep;
;             const char* a3 = a2 + kstep; const char* b3 = b2 + kstep;
;             if (last && has_next) S.a_ready(nxt);
;             if constexpr (SP2) {
;             PG8_LDB(B0, 0, 0); PG8_LDB(B1, 0, 1); PG8_SCHED; PG8_LDA(At, 0, 0); PG8_STAGE(PG8_SA(1, 1), a1 + hstepA, voffA);
;             PG8_WAIT_V(8); PG8_WAIT_L(0); PG8_BAR; PG8_MMA(0, 0, At, B0); PG8_MMA(0, 1, At, B1); PG8_BAR; PG8_SCHED;
;             PG8_LDA(At, 0, 1); PG8_STAGE(PG8_SB(0, 0), b2, voffB); PG8_STAGE(PG8_SB(0, 1), b2 + hstepB, voffB); PG8_STAGE(PG8_SA(0, 0), a2, voffA);
;             PG8_WAIT_V(8); PG8_WAIT_L(0); PG8_BAR; PG8_MMA(1, 0, At, B0); PG8_MMA(1, 1, At, B1); PG8_BAR; PG8_SCHED;
;             PG8_LDB(B0, 1, 0); PG8_LDB(B1, 1, 1); PG8_SCHED; PG8_LDA(At, 1, 0); PG8_STAGE(PG8_SA(0, 1), a2 + hstepA, voffA);
;             PG8_WAIT_V(8); PG8_WAIT_L(0); PG8_BAR; PG8_MMA(0, 0, At, B0); PG8_MMA(0, 1, At, B1); PG8_BAR; PG8_SCHED;
;             PG8_LDA(At, 1, 1); PG8_STAGE(PG8_SB(1, 0), b3, voffB); PG8_STAGE(PG8_SB(1, 1), b3 + hstepB, voffB); PG8_STAGE(PG8_SA(1, 0), a3, voffA);
;             PG8_WAIT_V(8); PG8_WAIT_L(0); PG8_BAR; PG8_MMA(1, 0, At, B0); PG8_MMA(1, 1, At, B1); PG8_BAR; PG8_SCHED;
	s_setprio 0
	v_add_u32_e32 v141, 0x18000, v139
	ds_read_b128 v[130:133], v141
	ds_read_b128 v[142:145], v141 offset:1024
	ds_read_b128 v[146:149], v141 offset:2048
	ds_read_b128 v[150:153], v141 offset:3072
	v_add_u32_e32 v141, 0x1c000, v139
	ds_read_b128 v[154:157], v141
	ds_read_b128 v[158:161], v141 offset:1024
	ds_read_b128 v[162:165], v141 offset:2048
	ds_read_b128 v[166:169], v141 offset:3072
	s_add_i32 s74, s17, 0x80000
	s_mov_b32 m0, s48
	ds_read_b128 v[170:173], v140 offset:32768
	ds_read_b128 v[174:177], v140 offset:33792
	ds_read_b128 v[178:181], v140 offset:34816
	ds_read_b128 v[182:185], v140 offset:35840
	ds_read_b128 v[186:189], v140 offset:36864
	ds_read_b128 v[190:193], v140 offset:37888
	ds_read_b128 v[200:203], v140 offset:38912
	ds_read_b128 v[206:209], v140 offset:39936
	s_mov_b32 m0, s47
	s_nop 0
	buffer_load_dwordx4 v135, s[4:7], s17 offen lds
	s_mov_b32 m0, s48
	s_nop 0
	buffer_load_dwordx4 v0, s[4:7], s74 offen lds
	s_mov_b32 m0, s49
	s_nop 0
	buffer_load_dwordx4 v135, s[4:7], s74 offen lds
	s_waitcnt vmcnt(8)
	s_waitcnt lgkmcnt(0)
	s_setprio 1
	s_barrier
	v_mfma_f32_16x16x32_bf16 v[126:129], v[130:133], v[170:173], v[126:129]
	v_mfma_f32_16x16x32_bf16 v[122:125], v[146:149], v[170:173], v[122:125]
	v_mfma_f32_16x16x32_bf16 v[106:109], v[146:149], v[178:181], v[106:109]
	v_mfma_f32_16x16x32_bf16 v[110:113], v[130:133], v[178:181], v[110:113]
	v_mfma_f32_16x16x32_bf16 v[94:97], v[130:133], v[186:189], v[94:97]
	v_mfma_f32_16x16x32_bf16 v[90:93], v[146:149], v[186:189], v[90:93]
	v_mfma_f32_16x16x32_bf16 v[74:77], v[146:149], v[200:203], v[74:77]
	v_mfma_f32_16x16x32_bf16 v[78:81], v[130:133], v[200:203], v[78:81]
	v_mfma_f32_16x16x32_bf16 v[126:129], v[142:145], v[174:177], v[126:129]
	v_mfma_f32_16x16x32_bf16 v[122:125], v[150:153], v[174:177], v[122:125]
	v_mfma_f32_16x16x32_bf16 v[106:109], v[150:153], v[182:185], v[106:109]
	v_mfma_f32_16x16x32_bf16 v[110:113], v[142:145], v[182:185], v[110:113]
	v_mfma_f32_16x16x32_bf16 v[94:97], v[142:145], v[190:193], v[94:97]
	v_mfma_f32_16x16x32_bf16 v[90:93], v[150:153], v[190:193], v[90:93]
	v_mfma_f32_16x16x32_bf16 v[74:77], v[150:153], v[206:209], v[74:77]
	v_mfma_f32_16x16x32_bf16 v[78:81], v[142:145], v[206:209], v[78:81]
	v_mfma_f32_16x16x32_bf16 v[118:121], v[154:157], v[170:173], v[118:121]
	v_mfma_f32_16x16x32_bf16 v[114:117], v[162:165], v[170:173], v[114:117]
	ds_read_b128 v[170:173], v140 offset:49152
	v_mfma_f32_16x16x32_bf16 v[98:101], v[162:165], v[178:181], v[98:101]
	v_mfma_f32_16x16x32_bf16 v[102:105], v[154:157], v[178:181], v[102:105]
	ds_read_b128 v[178:181], v140 offset:51200
	v_mfma_f32_16x16x32_bf16 v[86:89], v[154:157], v[186:189], v[86:89]
	v_mfma_f32_16x16x32_bf16 v[82:85], v[162:165], v[186:189], v[82:85]
	ds_read_b128 v[186:189], v140 offset:53248
	v_mfma_f32_16x16x32_bf16 v[66:69], v[162:165], v[200:203], v[66:69]
	v_mfma_f32_16x16x32_bf16 v[70:73], v[154:157], v[200:203], v[70:73]
	ds_read_b128 v[200:203], v140 offset:55296
	v_mfma_f32_16x16x32_bf16 v[118:121], v[158:161], v[174:177], v[118:121]
	v_mfma_f32_16x16x32_bf16 v[114:117], v[166:169], v[174:177], v[114:117]
	ds_read_b128 v[174:177], v140 offset:50176
	v_mfma_f32_16x16x32_bf16 v[98:101], v[166:169], v[182:185], v[98:101]
	v_mfma_f32_16x16x32_bf16 v[102:105], v[158:161], v[182:185], v[102:105]
	ds_read_b128 v[182:185], v140 offset:52224
	v_mfma_f32_16x16x32_bf16 v[86:89], v[158:161], v[190:193], v[86:89]
	v_mfma_f32_16x16x32_bf16 v[82:85], v[166:169], v[190:193], v[82:85]
	ds_read_b128 v[190:193], v140 offset:54272
	v_mfma_f32_16x16x32_bf16 v[66:69], v[166:169], v[206:209], v[66:69]
	v_mfma_f32_16x16x32_bf16 v[70:73], v[158:161], v[206:209], v[70:73]
	ds_read_b128 v[206:209], v140 offset:56320
	s_barrier
	s_setprio 0
	s_mov_b32 m0, s53
	s_add_i32 s74, s16, 0x80
	buffer_load_dwordx4 v134, s[40:43], s74 offen lds
	s_mov_b32 m0, s60
	s_add_i32 s16, s16, 0x80080
	buffer_load_dwordx4 v136, s[40:43], s74 offen lds
	s_mov_b32 m0, s63
	s_addk_i32 s17, 0x80
	buffer_load_dwordx4 v134, s[40:43], s16 offen lds
	s_mov_b32 m0, s66
	s_nop 0
	buffer_load_dwordx4 v136, s[40:43], s16 offen lds
	s_mov_b32 m0, s61
	s_nop 0
	buffer_load_dwordx4 v0, s[4:7], s17 offen lds
	s_waitcnt vmcnt(7)
	s_waitcnt lgkmcnt(0)
	s_setprio 1
	s_barrier
	v_mfma_f32_16x16x32_bf16 v[62:65], v[130:133], v[170:173], v[62:65]
	v_mfma_f32_16x16x32_bf16 v[58:61], v[146:149], v[170:173], v[58:61]
	v_mfma_f32_16x16x32_bf16 v[42:45], v[146:149], v[178:181], v[42:45]
	v_mfma_f32_16x16x32_bf16 v[46:49], v[130:133], v[178:181], v[46:49]
	v_mfma_f32_16x16x32_bf16 v[30:33], v[130:133], v[186:189], v[30:33]
	v_mfma_f32_16x16x32_bf16 v[26:29], v[146:149], v[186:189], v[26:29]
	v_mfma_f32_16x16x32_bf16 v[10:13], v[146:149], v[200:203], v[10:13]
	v_mfma_f32_16x16x32_bf16 v[14:17], v[130:133], v[200:203], v[14:17]
	v_mfma_f32_16x16x32_bf16 v[62:65], v[142:145], v[174:177], v[62:65]
	v_mfma_f32_16x16x32_bf16 v[58:61], v[150:153], v[174:177], v[58:61]
	v_mfma_f32_16x16x32_bf16 v[42:45], v[150:153], v[182:185], v[42:45]
	v_mfma_f32_16x16x32_bf16 v[46:49], v[142:145], v[182:185], v[46:49]
	v_mfma_f32_16x16x32_bf16 v[30:33], v[142:145], v[190:193], v[30:33]
	v_mfma_f32_16x16x32_bf16 v[26:29], v[150:153], v[190:193], v[26:29]
	v_mfma_f32_16x16x32_bf16 v[10:13], v[150:153], v[206:209], v[10:13]
	v_mfma_f32_16x16x32_bf16 v[14:17], v[142:145], v[206:209], v[14:17]
	v_mfma_f32_16x16x32_bf16 v[54:57], v[154:157], v[170:173], v[54:57]
	v_mfma_f32_16x16x32_bf16 v[50:53], v[162:165], v[170:173], v[50:53]
	v_mfma_f32_16x16x32_bf16 v[34:37], v[162:165], v[178:181], v[34:37]
	v_mfma_f32_16x16x32_bf16 v[38:41], v[154:157], v[178:181], v[38:41]
	v_mfma_f32_16x16x32_bf16 v[22:25], v[154:157], v[186:189], v[22:25]
	v_mfma_f32_16x16x32_bf16 v[18:21], v[162:165], v[186:189], v[18:21]
	v_mfma_f32_16x16x32_bf16 v[2:5], v[162:165], v[200:203], v[2:5]
	v_mfma_f32_16x16x32_bf16 v[6:9], v[154:157], v[200:203], v[6:9]
	v_mfma_f32_16x16x32_bf16 v[54:57], v[158:161], v[174:177], v[54:57]
	v_mfma_f32_16x16x32_bf16 v[50:53], v[166:169], v[174:177], v[50:53]
	v_mfma_f32_16x16x32_bf16 v[34:37], v[166:169], v[182:185], v[34:37]
	v_mfma_f32_16x16x32_bf16 v[38:41], v[158:161], v[182:185], v[38:41]
	v_mfma_f32_16x16x32_bf16 v[22:25], v[158:161], v[190:193], v[22:25]
	v_mfma_f32_16x16x32_bf16 v[18:21], v[166:169], v[190:193], v[18:21]
	v_mfma_f32_16x16x32_bf16 v[2:5], v[166:169], v[206:209], v[2:5]
	v_mfma_f32_16x16x32_bf16 v[6:9], v[158:161], v[206:209], v[6:9]
	s_barrier
	s_setprio 0
	s_add_i32 s73, s73, 2
	s_add_u32 s19, s19, 0x100
	s_addc_u32 s21, s21, 0
	s_cmp_gt_u32 s73, 29
	s_mov_b64 s[16:17], s[38:39]
	s_cbranch_scc0 .Ltrl_loop3

; #define PG8_STAGE(bufoff, gbase, voff) do { const int so_ = (int)(unsigned)((const char*)(gbase) - base_##voff); _Pragma("unroll") for (int _i = 0; _i < 2; ++_i) \
;         __builtin_amdgcn_raw_ptr_buffer_load_lds(rs_##voff, (PG8_LAS unsigned*)(lds + (bufoff) + ldsw + _i * 8192), 16, (int)(voff)[_i], so_, 0, 0); } while (0)
; #define PG8_LDA(dst, b, h) do { _Pragma("unroll") for (int m = 0; m < 4; ++m) _Pragma("unroll") for (int k = 0; k < 2; ++k) dst[m][k] = *(const PG8_LAS bf16x8*)(lds + PG8_SA(b, h) + aoff + m * 2048 + k * 1024); } while (0)
; #define PG8_WAIT_V(n) asm volatile("s_waitcnt vmcnt(" #n ")" ::: "memory")
; #define PG8_WAIT_L(n) asm volatile("s_waitcnt lgkmcnt(" #n ")" ::: "memory")
; template <class Epi, class Sched, bool ALIGN_EPI = false, bool SP2 = false>
; __device__ __forceinline__ void gemm_phase(PG8_LAS unsigned char* lds, const Gemm g, const Sched& S, const Epi& E, int tid_in) {
;     ...
;         for (int t = 0; t < nt; t += 2) {
;             const bool last = (t == nt - 2);
;             const char* a1 = cA + (size_t)(t + 1) * kstep;
;             const char* a2 = last ? nA : cA + (size_t)(t + 2) * kstep; const char* b2 = last ? nB : cB + (size_t)(t + 2) * kstep;
;             const char* a3 = a2 + kstep; const char* b3 = b2 + kstep;
;             if (last && has_next) S.a_ready(nxt);
;             if constexpr (SP2) {
;             PG8_LDB(B0, 0, 0); PG8_LDB(B1, 0, 1); PG8_SCHED; PG8_LDA(At, 0, 0); PG8_STAGE(PG8_SA(1, 1), a1 + hstepA, voffA);
;             PG8_WAIT_V(8); PG8_WAIT_L(0); PG8_BAR; PG8_MMA(0, 0, At, B0); PG8_MMA(0, 1, At, B1); PG8_BAR; PG8_SCHED;
;             PG8_LDA(At, 0, 1); PG8_STAGE(PG8_SB(0, 0), b2, voffB); PG8_STAGE(PG8_SB(0, 1), b2 + hstepB, voffB); PG8_STAGE(PG8_SA(0, 0), a2, voffA);
;             PG8_WAIT_V(8); PG8_WAIT_L(0); PG8_BAR; PG8_MMA(1, 0, At, B0); PG8_MMA(1, 1, At, B1); PG8_BAR; PG8_SCHED;
;             PG8_LDB(B0, 1, 0); PG8_LDB(B1, 1, 1); PG8_SCHED; PG8_LDA(At, 1, 0); PG8_STAGE(PG8_SA(0, 1), a2 + hstepA, voffA);
;             PG8_WAIT_V(8); PG8_WAIT_L(0); PG8_BAR; PG8_MMA(0, 0, At, B0); PG8_MMA(0, 1, At, B1); PG8_BAR; PG8_SCHED;
;             PG8_LDA(At, 1, 1); PG8_STAGE(PG8_SB(1, 0), b3, voffB); PG8_STAGE(PG8_SB(1, 1), b3 + hstepB, voffB); PG8_STAGE(PG8_SA(1, 0), a3, voffA);
;             PG8_WAIT_V(8); PG8_WAIT_L(0); PG8_BAR; PG8_MMA(1, 0, At, B0); PG8_MMA(1, 1, At, B1); PG8_BAR; PG8_SCHED;
.Ltrl_loop4:
	v_add_u32_e32 v133, 0x10000, v131
	ds_read_b128 v[134:137], v133
	ds_read_b128 v[138:141], v133 offset:1024
	ds_read_b128 v[142:145], v133 offset:2048
	ds_read_b128 v[146:149], v133 offset:3072
	v_add_u32_e32 v133, 0x14000, v131
	ds_read_b128 v[150:153], v133
	ds_read_b128 v[154:157], v133 offset:1024
	ds_read_b128 v[158:161], v133 offset:2048
	ds_read_b128 v[166:169], v133 offset:3072
	s_add_i32 s43, s38, s22
	s_add_i32 s42, s14, s22
	s_add_i32 s76, s12, s22
	s_addk_i32 s43, 0xff80
	s_sub_i32 s78, s43, 0x160000
	s_cmpk_eq_i32 s39, 0x54
	s_cselect_b32 s77, s16, s42
	s_mov_b32 m0, s68
	ds_read_b128 v[170:173], v132
	ds_read_b128 v[174:177], v132 offset:1024
	ds_read_b128 v[178:181], v132 offset:2048
	ds_read_b128 v[182:185], v132 offset:3072
	ds_read_b128 v[186:189], v132 offset:4096
	ds_read_b128 v[190:193], v132 offset:5120
	ds_read_b128 v[200:203], v132 offset:6144
	ds_read_b128 v[206:209], v132 offset:7168
	s_mov_b32 m0, s63
	s_nop 0
	buffer_load_dwordx4 v130, s[4:7], s78 offen lds
	s_mov_b32 m0, s68
	s_nop 0
	buffer_load_dwordx4 v0, s[4:7], s43 offen lds
	s_mov_b32 m0, s69
	s_nop 0
	buffer_load_dwordx4 v130, s[4:7], s43 offen lds
	s_waitcnt vmcnt(8)
	s_waitcnt lgkmcnt(0)
	s_setprio 1
	s_barrier
	v_mfma_f32_16x16x32_bf16 v[22:25], v[134:137], v[170:173], v[22:25]
	v_mfma_f32_16x16x32_bf16 v[14:17], v[142:145], v[170:173], v[14:17]
	v_mfma_f32_16x16x32_bf16 v[54:57], v[142:145], v[178:181], v[54:57]
	v_mfma_f32_16x16x32_bf16 v[74:77], v[134:137], v[178:181], v[74:77]
	v_mfma_f32_16x16x32_bf16 v[106:109], v[134:137], v[186:189], v[106:109]
	v_mfma_f32_16x16x32_bf16 v[102:105], v[142:145], v[186:189], v[102:105]
	v_mfma_f32_16x16x32_bf16 v[118:121], v[142:145], v[200:203], v[118:121]
	v_mfma_f32_16x16x32_bf16 v[122:125], v[134:137], v[200:203], v[122:125]
	v_mfma_f32_16x16x32_bf16 v[22:25], v[138:141], v[174:177], v[22:25]
	v_mfma_f32_16x16x32_bf16 v[14:17], v[146:149], v[174:177], v[14:17]
	v_mfma_f32_16x16x32_bf16 v[54:57], v[146:149], v[182:185], v[54:57]
	v_mfma_f32_16x16x32_bf16 v[74:77], v[138:141], v[182:185], v[74:77]
	v_mfma_f32_16x16x32_bf16 v[106:109], v[138:141], v[190:193], v[106:109]
	v_mfma_f32_16x16x32_bf16 v[102:105], v[146:149], v[190:193], v[102:105]
	v_mfma_f32_16x16x32_bf16 v[118:121], v[146:149], v[206:209], v[118:121]
	v_mfma_f32_16x16x32_bf16 v[122:125], v[138:141], v[206:209], v[122:125]
	v_mfma_f32_16x16x32_bf16 v[6:9], v[150:153], v[170:173], v[6:9]
	v_mfma_f32_16x16x32_bf16 v[18:21], v[158:161], v[170:173], v[18:21]
	ds_read_b128 v[170:173], v132 offset:16384
	v_mfma_f32_16x16x32_bf16 v[78:81], v[158:161], v[178:181], v[78:81]
	v_mfma_f32_16x16x32_bf16 v[50:53], v[150:153], v[178:181], v[50:53]
	ds_read_b128 v[178:181], v132 offset:18432
	v_mfma_f32_16x16x32_bf16 v[98:101], v[150:153], v[186:189], v[98:101]
	v_mfma_f32_16x16x32_bf16 v[110:113], v[158:161], v[186:189], v[110:113]
	ds_read_b128 v[186:189], v132 offset:20480
	v_mfma_f32_16x16x32_bf16 v[126:129], v[158:161], v[200:203], v[126:129]
	v_mfma_f32_16x16x32_bf16 v[114:117], v[150:153], v[200:203], v[114:117]
	ds_read_b128 v[200:203], v132 offset:22528
	v_mfma_f32_16x16x32_bf16 v[6:9], v[154:157], v[174:177], v[6:9]
	v_mfma_f32_16x16x32_bf16 v[18:21], v[166:169], v[174:177], v[18:21]
	ds_read_b128 v[174:177], v132 offset:17408
	v_mfma_f32_16x16x32_bf16 v[78:81], v[166:169], v[182:185], v[78:81]
	v_mfma_f32_16x16x32_bf16 v[50:53], v[154:157], v[182:185], v[50:53]
	ds_read_b128 v[182:185], v132 offset:19456
	v_mfma_f32_16x16x32_bf16 v[98:101], v[154:157], v[190:193], v[98:101]
	v_mfma_f32_16x16x32_bf16 v[110:113], v[166:169], v[190:193], v[110:113]
	ds_read_b128 v[190:193], v132 offset:21504
	v_mfma_f32_16x16x32_bf16 v[126:129], v[166:169], v[206:209], v[126:129]
	v_mfma_f32_16x16x32_bf16 v[114:117], v[154:157], v[206:209], v[114:117]
	ds_read_b128 v[206:209], v132 offset:23552
	s_barrier
	s_setprio 0
	s_cselect_b32 s76, s20, s76
	s_mov_b32 m0, s26
	s_mov_b32 s42, s6
	s_mov_b32 s43, s7
	s_sub_i32 s76, s76, s40
	buffer_load_dwordx4 v0, s[40:43], s76 offen lds
	s_mov_b32 m0, s44
	s_add_i32 s78, s76, 0x160000
	buffer_load_dwordx4 v130, s[40:43], s76 offen lds
	s_mov_b32 m0, s45
	s_sub_i32 s77, s77, s4
	buffer_load_dwordx4 v0, s[40:43], s78 offen lds
	s_mov_b32 m0, s46
	s_nop 0
	buffer_load_dwordx4 v130, s[40:43], s78 offen lds
	s_mov_b32 m0, s19
	s_nop 0
	buffer_load_dwordx4 v0, s[4:7], s77 offen lds
	s_waitcnt vmcnt(7)
	s_waitcnt lgkmcnt(0)
	s_setprio 1
	s_barrier
	v_mfma_f32_16x16x32_bf16 v[62:65], v[134:137], v[170:173], v[62:65]
	v_mfma_f32_16x16x32_bf16 v[46:49], v[142:145], v[170:173], v[46:49]
	v_mfma_f32_16x16x32_bf16 v[70:73], v[142:145], v[178:181], v[70:73]
	v_mfma_f32_16x16x32_bf16 v[82:85], v[134:137], v[178:181], v[82:85]
	v_mfma_f32_16x16x32_bf16 v[94:97], v[134:137], v[186:189], v[94:97]
	v_mfma_f32_16x16x32_bf16 v[90:93], v[142:145], v[186:189], v[90:93]
	v_mfma_f32_16x16x32_bf16 v[26:29], v[142:145], v[200:203], v[26:29]
	v_mfma_f32_16x16x32_bf16 v[38:41], v[134:137], v[200:203], v[38:41]
	v_mfma_f32_16x16x32_bf16 v[62:65], v[138:141], v[174:177], v[62:65]
	v_mfma_f32_16x16x32_bf16 v[46:49], v[146:149], v[174:177], v[46:49]
	v_mfma_f32_16x16x32_bf16 v[70:73], v[146:149], v[182:185], v[70:73]
	v_mfma_f32_16x16x32_bf16 v[82:85], v[138:141], v[182:185], v[82:85]
	v_mfma_f32_16x16x32_bf16 v[94:97], v[138:141], v[190:193], v[94:97]
	v_mfma_f32_16x16x32_bf16 v[90:93], v[146:149], v[190:193], v[90:93]
	v_mfma_f32_16x16x32_bf16 v[26:29], v[146:149], v[206:209], v[26:29]
	v_mfma_f32_16x16x32_bf16 v[38:41], v[138:141], v[206:209], v[38:41]
	v_mfma_f32_16x16x32_bf16 v[42:45], v[150:153], v[170:173], v[42:45]
	v_mfma_f32_16x16x32_bf16 v[30:33], v[158:161], v[170:173], v[30:33]
	v_mfma_f32_16x16x32_bf16 v[86:89], v[158:161], v[178:181], v[86:89]
	v_mfma_f32_16x16x32_bf16 v[66:69], v[150:153], v[178:181], v[66:69]
	v_mfma_f32_16x16x32_bf16 v[58:61], v[150:153], v[186:189], v[58:61]
	v_mfma_f32_16x16x32_bf16 v[34:37], v[158:161], v[186:189], v[34:37]
	v_mfma_f32_16x16x32_bf16 v[2:5], v[158:161], v[200:203], v[2:5]
	v_mfma_f32_16x16x32_bf16 v[10:13], v[150:153], v[200:203], v[10:13]
	v_mfma_f32_16x16x32_bf16 v[42:45], v[154:157], v[174:177], v[42:45]
	v_mfma_f32_16x16x32_bf16 v[30:33], v[166:169], v[174:177], v[30:33]
	v_mfma_f32_16x16x32_bf16 v[86:89], v[166:169], v[182:185], v[86:89]
	v_mfma_f32_16x16x32_bf16 v[66:69], v[154:157], v[182:185], v[66:69]
	v_mfma_f32_16x16x32_bf16 v[58:61], v[154:157], v[190:193], v[58:61]
	v_mfma_f32_16x16x32_bf16 v[34:37], v[166:169], v[190:193], v[34:37]
	v_mfma_f32_16x16x32_bf16 v[2:5], v[166:169], v[206:209], v[2:5]
	v_mfma_f32_16x16x32_bf16 v[10:13], v[154:157], v[206:209], v[10:13]
	s_barrier
; #define PG8_STAGE(bufoff, gbase, voff) do { const int so_ = (int)(unsigned)((const char*)(gbase) - base_##voff); _Pragma("unroll") for (int _i = 0; _i < 2; ++_i) \
;         __builtin_amdgcn_raw_ptr_buffer_load_lds(rs_##voff, (PG8_LAS unsigned*)(lds + (bufoff) + ldsw + _i * 8192), 16, (int)(voff)[_i], so_, 0, 0); } while (0)
; #define PG8_LDA(dst, b, h) do { _Pragma("unroll") for (int m = 0; m < 4; ++m) _Pragma("unroll") for (int k = 0; k < 2; ++k) dst[m][k] = *(const PG8_LAS bf16x8*)(lds + PG8_SA(b, h) + aoff + m * 2048 + k * 1024); } while (0)
; #define PG8_WAIT_V(n) asm volatile("s_waitcnt vmcnt(" #n ")" ::: "memory")
; #define PG8_WAIT_L(n) asm volatile("s_waitcnt lgkmcnt(" #n ")" ::: "memory")
; template <class Epi, class Sched, bool ALIGN_EPI = false, bool SP2 = false>
; __device__ __forceinline__ void gemm_phase(PG8_LAS unsigned char* lds, const Gemm g, const Sched& S, const Epi& E, int tid_in) {
;     ...
;         for (int t = 0; t < nt; t += 2) {
;             const bool last = (t == nt - 2);
;             const char* a1 = cA + (size_t)(t + 1) * kstep;
;             const char* a2 = last ? nA : cA + (size_t)(t + 2) * kstep; const char* b2 = last ? nB : cB + (size_t)(t + 2) * kstep;
;             const char* a3 = a2 + kstep; const char* b3 = b2 + kstep;
;             if (last && has_next) S.a_ready(nxt);
;             if constexpr (SP2) {
;             PG8_LDB(B0, 0, 0); PG8_LDB(B1, 0, 1); PG8_SCHED; PG8_LDA(At, 0, 0); PG8_STAGE(PG8_SA(1, 1), a1 + hstepA, voffA);
;             PG8_WAIT_V(8); PG8_WAIT_L(0); PG8_BAR; PG8_MMA(0, 0, At, B0); PG8_MMA(0, 1, At, B1); PG8_BAR; PG8_SCHED;
;             PG8_LDA(At, 0, 1); PG8_STAGE(PG8_SB(0, 0), b2, voffB); PG8_STAGE(PG8_SB(0, 1), b2 + hstepB, voffB); PG8_STAGE(PG8_SA(0, 0), a2, voffA);
;             PG8_WAIT_V(8); PG8_WAIT_L(0); PG8_BAR; PG8_MMA(1, 0, At, B0); PG8_MMA(1, 1, At, B1); PG8_BAR; PG8_SCHED;
;             PG8_LDB(B0, 1, 0); PG8_LDB(B1, 1, 1); PG8_SCHED; PG8_LDA(At, 1, 0); PG8_STAGE(PG8_SA(0, 1), a2 + hstepA, voffA);
;             PG8_WAIT_V(8); PG8_WAIT_L(0); PG8_BAR; PG8_MMA(0, 0, At, B0); PG8_MMA(0, 1, At, B1); PG8_BAR; PG8_SCHED;
;             PG8_LDA(At, 1, 1); PG8_STAGE(PG8_SB(1, 0), b3, voffB); PG8_STAGE(PG8_SB(1, 1), b3 + hstepB, voffB); PG8_STAGE(PG8_SA(1, 0), a3, voffA);
;             PG8_WAIT_V(8); PG8_WAIT_L(0); PG8_BAR; PG8_MMA(1, 0, At, B0); PG8_MMA(1, 1, At, B1); PG8_BAR; PG8_SCHED;
	s_setprio 0
	v_add_u32_e32 v133, 0x18000, v131
	ds_read_b128 v[134:137], v133
	ds_read_b128 v[138:141], v133 offset:1024
	ds_read_b128 v[142:145], v133 offset:2048
	ds_read_b128 v[146:149], v133 offset:3072
	v_add_u32_e32 v133, 0x1c000, v131
	ds_read_b128 v[150:153], v133
	ds_read_b128 v[154:157], v133 offset:1024
	ds_read_b128 v[158:161], v133 offset:2048
	ds_read_b128 v[166:169], v133 offset:3072
	s_add_i32 s78, s77, 0x160000
	s_mov_b32 m0, s48
	ds_read_b128 v[170:173], v132 offset:32768
	ds_read_b128 v[174:177], v132 offset:33792
	ds_read_b128 v[178:181], v132 offset:34816
	ds_read_b128 v[182:185], v132 offset:35840
	ds_read_b128 v[186:189], v132 offset:36864
	ds_read_b128 v[190:193], v132 offset:37888
	ds_read_b128 v[200:203], v132 offset:38912
	ds_read_b128 v[206:209], v132 offset:39936
	s_mov_b32 m0, s47
	s_nop 0
	buffer_load_dwordx4 v130, s[4:7], s77 offen lds
	s_mov_b32 m0, s48
	s_nop 0
	buffer_load_dwordx4 v0, s[4:7], s78 offen lds
	s_mov_b32 m0, s49
	s_nop 0
	buffer_load_dwordx4 v130, s[4:7], s78 offen lds
	s_waitcnt vmcnt(8)
	s_waitcnt lgkmcnt(0)
	s_setprio 1
	s_barrier
	v_mfma_f32_16x16x32_bf16 v[22:25], v[134:137], v[170:173], v[22:25]
	v_mfma_f32_16x16x32_bf16 v[14:17], v[142:145], v[170:173], v[14:17]
	v_mfma_f32_16x16x32_bf16 v[54:57], v[142:145], v[178:181], v[54:57]
	v_mfma_f32_16x16x32_bf16 v[74:77], v[134:137], v[178:181], v[74:77]
	v_mfma_f32_16x16x32_bf16 v[106:109], v[134:137], v[186:189], v[106:109]
	v_mfma_f32_16x16x32_bf16 v[102:105], v[142:145], v[186:189], v[102:105]
	v_mfma_f32_16x16x32_bf16 v[118:121], v[142:145], v[200:203], v[118:121]
	v_mfma_f32_16x16x32_bf16 v[122:125], v[134:137], v[200:203], v[122:125]
	v_mfma_f32_16x16x32_bf16 v[22:25], v[138:141], v[174:177], v[22:25]
	v_mfma_f32_16x16x32_bf16 v[14:17], v[146:149], v[174:177], v[14:17]
	v_mfma_f32_16x16x32_bf16 v[54:57], v[146:149], v[182:185], v[54:57]
	v_mfma_f32_16x16x32_bf16 v[74:77], v[138:141], v[182:185], v[74:77]
	v_mfma_f32_16x16x32_bf16 v[106:109], v[138:141], v[190:193], v[106:109]
	v_mfma_f32_16x16x32_bf16 v[102:105], v[146:149], v[190:193], v[102:105]
	v_mfma_f32_16x16x32_bf16 v[118:121], v[146:149], v[206:209], v[118:121]
	v_mfma_f32_16x16x32_bf16 v[122:125], v[138:141], v[206:209], v[122:125]
	v_mfma_f32_16x16x32_bf16 v[6:9], v[150:153], v[170:173], v[6:9]
	v_mfma_f32_16x16x32_bf16 v[18:21], v[158:161], v[170:173], v[18:21]
	ds_read_b128 v[170:173], v132 offset:49152
	v_mfma_f32_16x16x32_bf16 v[78:81], v[158:161], v[178:181], v[78:81]
	v_mfma_f32_16x16x32_bf16 v[50:53], v[150:153], v[178:181], v[50:53]
	ds_read_b128 v[178:181], v132 offset:51200
	v_mfma_f32_16x16x32_bf16 v[98:101], v[150:153], v[186:189], v[98:101]
	v_mfma_f32_16x16x32_bf16 v[110:113], v[158:161], v[186:189], v[110:113]
	ds_read_b128 v[186:189], v132 offset:53248
	v_mfma_f32_16x16x32_bf16 v[126:129], v[158:161], v[200:203], v[126:129]
	v_mfma_f32_16x16x32_bf16 v[114:117], v[150:153], v[200:203], v[114:117]
	ds_read_b128 v[200:203], v132 offset:55296
	v_mfma_f32_16x16x32_bf16 v[6:9], v[154:157], v[174:177], v[6:9]
	v_mfma_f32_16x16x32_bf16 v[18:21], v[166:169], v[174:177], v[18:21]
	ds_read_b128 v[174:177], v132 offset:50176
	v_mfma_f32_16x16x32_bf16 v[78:81], v[166:169], v[182:185], v[78:81]
	v_mfma_f32_16x16x32_bf16 v[50:53], v[154:157], v[182:185], v[50:53]
	ds_read_b128 v[182:185], v132 offset:52224
	v_mfma_f32_16x16x32_bf16 v[98:101], v[154:157], v[190:193], v[98:101]
	v_mfma_f32_16x16x32_bf16 v[110:113], v[166:169], v[190:193], v[110:113]
	ds_read_b128 v[190:193], v132 offset:54272
	v_mfma_f32_16x16x32_bf16 v[126:129], v[166:169], v[206:209], v[126:129]
	v_mfma_f32_16x16x32_bf16 v[114:117], v[154:157], v[206:209], v[114:117]
	ds_read_b128 v[206:209], v132 offset:56320
	s_barrier
	s_setprio 0
	s_mov_b32 m0, s60
	s_add_i32 s78, s76, 0x80
	buffer_load_dwordx4 v0, s[40:43], s78 offen lds
	s_mov_b32 m0, s61
	s_add_i32 s76, s76, 0x160080
	buffer_load_dwordx4 v130, s[40:43], s78 offen lds
	s_mov_b32 m0, s66
	s_addk_i32 s77, 0x80
	buffer_load_dwordx4 v0, s[40:43], s76 offen lds
	s_mov_b32 m0, s67
	s_nop 0
	buffer_load_dwordx4 v130, s[40:43], s76 offen lds
	s_mov_b32 m0, s62
	s_nop 0
	buffer_load_dwordx4 v0, s[4:7], s77 offen lds
	s_waitcnt vmcnt(7)
	s_waitcnt lgkmcnt(0)
	s_setprio 1
	s_barrier
	v_mfma_f32_16x16x32_bf16 v[62:65], v[134:137], v[170:173], v[62:65]
	v_mfma_f32_16x16x32_bf16 v[46:49], v[142:145], v[170:173], v[46:49]
	v_mfma_f32_16x16x32_bf16 v[70:73], v[142:145], v[178:181], v[70:73]
	v_mfma_f32_16x16x32_bf16 v[82:85], v[134:137], v[178:181], v[82:85]
	v_mfma_f32_16x16x32_bf16 v[94:97], v[134:137], v[186:189], v[94:97]
	v_mfma_f32_16x16x32_bf16 v[90:93], v[142:145], v[186:189], v[90:93]
	v_mfma_f32_16x16x32_bf16 v[26:29], v[142:145], v[200:203], v[26:29]
	v_mfma_f32_16x16x32_bf16 v[38:41], v[134:137], v[200:203], v[38:41]
	v_mfma_f32_16x16x32_bf16 v[62:65], v[138:141], v[174:177], v[62:65]
	v_mfma_f32_16x16x32_bf16 v[46:49], v[146:149], v[174:177], v[46:49]
	v_mfma_f32_16x16x32_bf16 v[70:73], v[146:149], v[182:185], v[70:73]
	v_mfma_f32_16x16x32_bf16 v[82:85], v[138:141], v[182:185], v[82:85]
	v_mfma_f32_16x16x32_bf16 v[94:97], v[138:141], v[190:193], v[94:97]
	v_mfma_f32_16x16x32_bf16 v[90:93], v[146:149], v[190:193], v[90:93]
	v_mfma_f32_16x16x32_bf16 v[26:29], v[146:149], v[206:209], v[26:29]
	v_mfma_f32_16x16x32_bf16 v[38:41], v[138:141], v[206:209], v[38:41]
	v_mfma_f32_16x16x32_bf16 v[42:45], v[150:153], v[170:173], v[42:45]
	v_mfma_f32_16x16x32_bf16 v[30:33], v[158:161], v[170:173], v[30:33]
	v_mfma_f32_16x16x32_bf16 v[86:89], v[158:161], v[178:181], v[86:89]
	v_mfma_f32_16x16x32_bf16 v[66:69], v[150:153], v[178:181], v[66:69]
	v_mfma_f32_16x16x32_bf16 v[58:61], v[150:153], v[186:189], v[58:61]
	v_mfma_f32_16x16x32_bf16 v[34:37], v[158:161], v[186:189], v[34:37]
	v_mfma_f32_16x16x32_bf16 v[2:5], v[158:161], v[200:203], v[2:5]
	v_mfma_f32_16x16x32_bf16 v[10:13], v[150:153], v[200:203], v[10:13]
	v_mfma_f32_16x16x32_bf16 v[42:45], v[154:157], v[174:177], v[42:45]
	v_mfma_f32_16x16x32_bf16 v[30:33], v[166:169], v[174:177], v[30:33]
	v_mfma_f32_16x16x32_bf16 v[86:89], v[166:169], v[182:185], v[86:89]
	v_mfma_f32_16x16x32_bf16 v[66:69], v[154:157], v[182:185], v[66:69]
	v_mfma_f32_16x16x32_bf16 v[58:61], v[154:157], v[190:193], v[58:61]
	v_mfma_f32_16x16x32_bf16 v[34:37], v[166:169], v[190:193], v[34:37]
	v_mfma_f32_16x16x32_bf16 v[2:5], v[166:169], v[206:209], v[2:5]
	v_mfma_f32_16x16x32_bf16 v[10:13], v[154:157], v[206:209], v[10:13]
	s_barrier
	s_setprio 0
	s_add_i32 s39, s39, 2
	s_add_u32 s22, s22, 0x100
	s_addc_u32 s23, s23, 0
	s_cmpk_gt_u32 s39, 0x55
	s_cbranch_scc0 .Ltrl_loop4
